# v8 + responsibility-split L2 prefetch, two dword LDS-DMA touches per wave per iteration (12 lanes each): K-tile t+3 after load segment 1, K-tile t+4 after load segment 3
# baseline (speedup 1.0000x reference)
.LBB0_340:
	s_and_b32 s98, s55, 3
	s_and_b32 s99, s54, 7
	s_lshl_b32 s98, s98, 6
	s_lshl_b32 s99, s99, 5
	v_and_b32_e32 v244, 63, v0
	v_mul_u32_u24_e32 v245, 86, v244
	v_lshrrev_b32_e32 v245, 10, v245
	v_mul_u32_u24_e32 v245, 12, v245
	v_sub_u32_e32 v244, v244, v245
	v_lshrrev_b32_e32 v245, 6, v0
	v_mad_u32_u24 v244, v245, 12, v244
	v_cmp_gt_u32_e32 vcc, 64, v244
	v_add_u32_e32 v245, s98, v244
	v_subrev_u32_e32 v247, 64, v244
	v_add_u32_e32 v248, s99, v247
	v_cndmask_b32_e32 v245, v248, v245, vcc
	v_lshlrev_b32_e32 v245, 13, v245
	v_add_u32_e32 v244, 0x80, v245
	v_mov_b32_e32 v245, 0
	v_mov_b32_e32 v246, s12
	v_mov_b32_e32 v247, s13
	v_mov_b32_e32 v248, s14
	v_mov_b32_e32 v249, s15
	v_cndmask_b32_e32 v246, v248, v246, vcc
	v_cndmask_b32_e32 v247, v249, v247, vcc
	v_lshl_add_u64 v[242:243], v[246:247], 0, v[244:245]
	v_add_u32_e32 v252, 0x10000, v159
	s_add_u32 s12, s12, 0x100080
	s_addc_u32 s13, s13, 0
	s_add_u32 s0, s14, 0x100
	v_mov_b32_e32 v2, 0
	s_addc_u32 s1, s15, 0
	s_mov_b32 s39, -2
	v_mov_b32_e32 v3, v2
	v_mov_b32_e32 v4, v2
	v_mov_b32_e32 v5, v2
	v_mov_b32_e32 v6, v2
	v_mov_b32_e32 v7, v2
	v_mov_b32_e32 v8, v2
	v_mov_b32_e32 v9, v2
	v_mov_b32_e32 v18, v2
	v_mov_b32_e32 v19, v2
	v_mov_b32_e32 v20, v2
	v_mov_b32_e32 v21, v2
	v_mov_b32_e32 v22, v2
	v_mov_b32_e32 v23, v2
	v_mov_b32_e32 v24, v2
	v_mov_b32_e32 v25, v2
	v_mov_b32_e32 v34, v2
	v_mov_b32_e32 v35, v2
	v_mov_b32_e32 v36, v2
	v_mov_b32_e32 v37, v2
	v_mov_b32_e32 v38, v2
	v_mov_b32_e32 v39, v2
	v_mov_b32_e32 v40, v2
	v_mov_b32_e32 v41, v2
	v_mov_b32_e32 v50, v2
	v_mov_b32_e32 v51, v2
	v_mov_b32_e32 v52, v2
	v_mov_b32_e32 v53, v2
	v_mov_b32_e32 v54, v2
	v_mov_b32_e32 v55, v2
	v_mov_b32_e32 v56, v2
	v_mov_b32_e32 v57, v2
	v_mov_b32_e32 v10, v2
	v_mov_b32_e32 v11, v2
	v_mov_b32_e32 v12, v2
	v_mov_b32_e32 v13, v2
	v_mov_b32_e32 v14, v2
	v_mov_b32_e32 v15, v2
	v_mov_b32_e32 v16, v2
	v_mov_b32_e32 v17, v2
	v_mov_b32_e32 v26, v2
	v_mov_b32_e32 v27, v2
	v_mov_b32_e32 v28, v2
	v_mov_b32_e32 v29, v2
	v_mov_b32_e32 v30, v2
	v_mov_b32_e32 v31, v2
	v_mov_b32_e32 v32, v2
	v_mov_b32_e32 v33, v2
	v_mov_b32_e32 v42, v2
	v_mov_b32_e32 v43, v2
	v_mov_b32_e32 v44, v2
	v_mov_b32_e32 v45, v2
	v_mov_b32_e32 v46, v2
	v_mov_b32_e32 v47, v2
	v_mov_b32_e32 v48, v2
	v_mov_b32_e32 v49, v2
	v_mov_b32_e32 v58, v2
	v_mov_b32_e32 v59, v2
	v_mov_b32_e32 v60, v2
	v_mov_b32_e32 v61, v2
	v_mov_b32_e32 v62, v2
	v_mov_b32_e32 v63, v2
	v_mov_b32_e32 v64, v2
	v_mov_b32_e32 v65, v2
	v_mov_b32_e32 v66, v2
	v_mov_b32_e32 v67, v2
	v_mov_b32_e32 v68, v2
	v_mov_b32_e32 v69, v2
	v_mov_b32_e32 v70, v2
	v_mov_b32_e32 v71, v2
	v_mov_b32_e32 v72, v2
	v_mov_b32_e32 v73, v2
	v_mov_b32_e32 v82, v2
	v_mov_b32_e32 v83, v2
	v_mov_b32_e32 v84, v2
	v_mov_b32_e32 v85, v2
	v_mov_b32_e32 v86, v2
	v_mov_b32_e32 v87, v2
	v_mov_b32_e32 v88, v2
	v_mov_b32_e32 v89, v2
	v_mov_b32_e32 v98, v2
	v_mov_b32_e32 v99, v2
	v_mov_b32_e32 v100, v2
	v_mov_b32_e32 v101, v2
	v_mov_b32_e32 v102, v2
	v_mov_b32_e32 v103, v2
	v_mov_b32_e32 v104, v2
	v_mov_b32_e32 v105, v2
	v_mov_b32_e32 v114, v2
	v_mov_b32_e32 v115, v2
	v_mov_b32_e32 v116, v2
	v_mov_b32_e32 v117, v2
	v_mov_b32_e32 v118, v2
	v_mov_b32_e32 v119, v2
	v_mov_b32_e32 v120, v2
	v_mov_b32_e32 v121, v2
	v_mov_b32_e32 v74, v2
	v_mov_b32_e32 v75, v2
	v_mov_b32_e32 v76, v2
	v_mov_b32_e32 v77, v2
	v_mov_b32_e32 v78, v2
	v_mov_b32_e32 v79, v2
	v_mov_b32_e32 v80, v2
	v_mov_b32_e32 v81, v2
	v_mov_b32_e32 v90, v2
	v_mov_b32_e32 v91, v2
	v_mov_b32_e32 v92, v2
	v_mov_b32_e32 v93, v2
	v_mov_b32_e32 v94, v2
	v_mov_b32_e32 v95, v2
	v_mov_b32_e32 v96, v2
	v_mov_b32_e32 v97, v2
	v_mov_b32_e32 v106, v2
	v_mov_b32_e32 v107, v2
	v_mov_b32_e32 v108, v2
	v_mov_b32_e32 v109, v2
	v_mov_b32_e32 v110, v2
	v_mov_b32_e32 v111, v2
	v_mov_b32_e32 v112, v2
	v_mov_b32_e32 v113, v2
	v_mov_b32_e32 v122, v2
	v_mov_b32_e32 v123, v2
	v_mov_b32_e32 v124, v2
	v_mov_b32_e32 v125, v2
	v_mov_b32_e32 v126, v2
	v_mov_b32_e32 v127, v2
	v_mov_b32_e32 v128, v2
	v_mov_b32_e32 v129, v2
.LBB0_341:
	s_add_u32 s14, s12, 0xfff00080
	s_addc_u32 s15, s13, -1
	s_cmp_eq_u32 s39, 60
	s_cselect_b32 s17, s51, s15
	s_cselect_b32 s16, s50, s14
	s_cselect_b32 s15, s53, s1
	s_cselect_b32 s14, s52, s0
	s_cmp_lt_i32 s39, 58
	s_cselect_b32 s100, 0x100, 0
	s_mov_b32 s101, 0
	v_lshl_add_u64 v[242:243], v[242:243], 0, s[100:101]
	s_add_i32 m0, s8, 0xc000
	ds_read_b128 v[152:155], v252
	ds_read_b128 v[162:165], v252 offset:1024
	global_load_lds_dwordx4 v148, s[12:13]
	s_add_i32 m0, s8, 0xe000
	ds_read_b128 v[166:169], v252 offset:2048
	ds_read_b128 v[170:173], v252 offset:3072
	global_load_lds_dwordx4 v150, s[12:13]
	ds_read_b128 v[174:177], v252 offset:16384
	ds_read_b128 v[182:185], v252 offset:17408
	ds_read_b128 v[186:189], v252 offset:18432
	ds_read_b128 v[190:193], v252 offset:19456
	ds_read_b128 v[194:197], v161
	ds_read_b128 v[198:201], v161 offset:1024
	ds_read_b128 v[202:205], v161 offset:2048
	ds_read_b128 v[206:209], v161 offset:3072
	ds_read_b128 v[210:213], v161 offset:4096
	ds_read_b128 v[214:217], v161 offset:5120
	ds_read_b128 v[218:221], v161 offset:6144
	ds_read_b128 v[222:225], v161 offset:7168
	s_waitcnt vmcnt(9)
	s_mov_b32 m0, 0x21800
	s_mov_b64 exec, 0xfff
	s_waitcnt lgkmcnt(0)
	global_load_lds_dword v[242:243], off
	s_mov_b64 exec, -1
	s_barrier
	v_mfma_f32_16x16x32_bf16 v[126:129], v[152:155], v[194:197], v[126:129]
	v_mfma_f32_16x16x32_bf16 v[126:129], v[162:165], v[198:201], v[126:129]
	v_mfma_f32_16x16x32_bf16 v[122:125], v[166:169], v[194:197], v[122:125]
	v_mfma_f32_16x16x32_bf16 v[122:125], v[170:173], v[198:201], v[122:125]
	v_mfma_f32_16x16x32_bf16 v[110:113], v[152:155], v[202:205], v[110:113]
	v_mfma_f32_16x16x32_bf16 v[110:113], v[162:165], v[206:209], v[110:113]
	v_mfma_f32_16x16x32_bf16 v[106:109], v[166:169], v[202:205], v[106:109]
	v_mfma_f32_16x16x32_bf16 v[106:109], v[170:173], v[206:209], v[106:109]
	v_mfma_f32_16x16x32_bf16 v[94:97], v[152:155], v[210:213], v[94:97]
	v_mfma_f32_16x16x32_bf16 v[94:97], v[162:165], v[214:217], v[94:97]
	v_mfma_f32_16x16x32_bf16 v[90:93], v[166:169], v[210:213], v[90:93]
	v_mfma_f32_16x16x32_bf16 v[90:93], v[170:173], v[214:217], v[90:93]
	v_mfma_f32_16x16x32_bf16 v[78:81], v[152:155], v[218:221], v[78:81]
	v_mfma_f32_16x16x32_bf16 v[78:81], v[162:165], v[222:225], v[78:81]
	v_mfma_f32_16x16x32_bf16 v[74:77], v[166:169], v[218:221], v[74:77]
	v_mfma_f32_16x16x32_bf16 v[74:77], v[170:173], v[222:225], v[74:77]
	v_mfma_f32_16x16x32_bf16 v[118:121], v[174:177], v[194:197], v[118:121]
	v_mfma_f32_16x16x32_bf16 v[118:121], v[182:185], v[198:201], v[118:121]
	v_mfma_f32_16x16x32_bf16 v[114:117], v[186:189], v[194:197], v[114:117]
	v_mfma_f32_16x16x32_bf16 v[114:117], v[190:193], v[198:201], v[114:117]
	v_mfma_f32_16x16x32_bf16 v[102:105], v[174:177], v[202:205], v[102:105]
	v_mfma_f32_16x16x32_bf16 v[102:105], v[182:185], v[206:209], v[102:105]
	v_mfma_f32_16x16x32_bf16 v[98:101], v[186:189], v[202:205], v[98:101]
	v_mfma_f32_16x16x32_bf16 v[98:101], v[190:193], v[206:209], v[98:101]
	v_mfma_f32_16x16x32_bf16 v[86:89], v[174:177], v[210:213], v[86:89]
	v_mfma_f32_16x16x32_bf16 v[86:89], v[182:185], v[214:217], v[86:89]
	v_mfma_f32_16x16x32_bf16 v[82:85], v[186:189], v[210:213], v[82:85]
	v_mfma_f32_16x16x32_bf16 v[82:85], v[190:193], v[214:217], v[82:85]
	v_mfma_f32_16x16x32_bf16 v[70:73], v[174:177], v[218:221], v[70:73]
	v_mfma_f32_16x16x32_bf16 v[70:73], v[182:185], v[222:225], v[70:73]
	v_mfma_f32_16x16x32_bf16 v[66:69], v[186:189], v[218:221], v[66:69]
	v_mfma_f32_16x16x32_bf16 v[66:69], v[190:193], v[222:225], v[66:69]
	s_barrier
	s_add_i32 m0, s28, 0x10000
	ds_read_b128 v[194:197], v161 offset:16384
	ds_read_b128 v[198:201], v161 offset:17408
	global_load_lds_dwordx4 v144, s[14:15]
	s_add_i32 m0, s28, 0x12000
	s_add_u32 s98, s14, 0x100000
	s_addc_u32 s99, s15, 0
	ds_read_b128 v[202:205], v161 offset:18432
	global_load_lds_dwordx4 v140, s[14:15]
	s_add_i32 m0, s28, 0x14000
	ds_read_b128 v[206:209], v161 offset:19456
	ds_read_b128 v[210:213], v161 offset:20480
	global_load_lds_dwordx4 v144, s[98:99]
	s_add_i32 m0, s28, 0x16000
	ds_read_b128 v[214:217], v161 offset:21504
	ds_read_b128 v[218:221], v161 offset:22528
	global_load_lds_dwordx4 v140, s[98:99]
	s_mov_b32 m0, s8
	ds_read_b128 v[222:225], v161 offset:23552
	global_load_lds_dwordx4 v146, s[16:17]
	s_mov_b32 m0, s9
	s_nop 0
	global_load_lds_dwordx4 v142, s[16:17]
	s_waitcnt vmcnt(9)
	s_waitcnt lgkmcnt(0)
	s_barrier
	v_mfma_f32_16x16x32_bf16 v[62:65], v[152:155], v[194:197], v[62:65]
	v_mfma_f32_16x16x32_bf16 v[62:65], v[162:165], v[198:201], v[62:65]
	v_mfma_f32_16x16x32_bf16 v[58:61], v[166:169], v[194:197], v[58:61]
	v_mfma_f32_16x16x32_bf16 v[58:61], v[170:173], v[198:201], v[58:61]
	v_mfma_f32_16x16x32_bf16 v[46:49], v[152:155], v[202:205], v[46:49]
	v_mfma_f32_16x16x32_bf16 v[46:49], v[162:165], v[206:209], v[46:49]
	v_mfma_f32_16x16x32_bf16 v[42:45], v[166:169], v[202:205], v[42:45]
	v_mfma_f32_16x16x32_bf16 v[42:45], v[170:173], v[206:209], v[42:45]
	v_mfma_f32_16x16x32_bf16 v[30:33], v[152:155], v[210:213], v[30:33]
	v_mfma_f32_16x16x32_bf16 v[30:33], v[162:165], v[214:217], v[30:33]
	v_mfma_f32_16x16x32_bf16 v[26:29], v[166:169], v[210:213], v[26:29]
	v_mfma_f32_16x16x32_bf16 v[26:29], v[170:173], v[214:217], v[26:29]
	v_mfma_f32_16x16x32_bf16 v[14:17], v[152:155], v[218:221], v[14:17]
	v_mfma_f32_16x16x32_bf16 v[14:17], v[162:165], v[222:225], v[14:17]
	v_mfma_f32_16x16x32_bf16 v[10:13], v[166:169], v[218:221], v[10:13]
	v_mfma_f32_16x16x32_bf16 v[10:13], v[170:173], v[222:225], v[10:13]
	v_mfma_f32_16x16x32_bf16 v[54:57], v[174:177], v[194:197], v[54:57]
	v_mfma_f32_16x16x32_bf16 v[54:57], v[182:185], v[198:201], v[54:57]
	v_mfma_f32_16x16x32_bf16 v[50:53], v[186:189], v[194:197], v[50:53]
	v_mfma_f32_16x16x32_bf16 v[50:53], v[190:193], v[198:201], v[50:53]
	v_mfma_f32_16x16x32_bf16 v[38:41], v[174:177], v[202:205], v[38:41]
	v_mfma_f32_16x16x32_bf16 v[38:41], v[182:185], v[206:209], v[38:41]
	v_mfma_f32_16x16x32_bf16 v[34:37], v[186:189], v[202:205], v[34:37]
	v_mfma_f32_16x16x32_bf16 v[34:37], v[190:193], v[206:209], v[34:37]
	v_mfma_f32_16x16x32_bf16 v[22:25], v[174:177], v[210:213], v[22:25]
	v_mfma_f32_16x16x32_bf16 v[22:25], v[182:185], v[214:217], v[22:25]
	v_mfma_f32_16x16x32_bf16 v[18:21], v[186:189], v[210:213], v[18:21]
	v_mfma_f32_16x16x32_bf16 v[18:21], v[190:193], v[214:217], v[18:21]
	v_mfma_f32_16x16x32_bf16 v[6:9], v[174:177], v[218:221], v[6:9]
	v_mfma_f32_16x16x32_bf16 v[6:9], v[182:185], v[222:225], v[6:9]
	v_mfma_f32_16x16x32_bf16 v[2:5], v[186:189], v[218:221], v[2:5]
	v_mfma_f32_16x16x32_bf16 v[2:5], v[190:193], v[222:225], v[2:5]
	s_barrier
	s_add_u32 s100, s16, 0x100000
	s_addc_u32 s101, s17, 0
	s_mov_b32 m0, s29
	ds_read_b128 v[152:155], v252 offset:32768
	ds_read_b128 v[162:165], v252 offset:33792
	global_load_lds_dwordx4 v146, s[100:101]
	s_mov_b32 m0, s36
	ds_read_b128 v[166:169], v252 offset:34816
	ds_read_b128 v[170:173], v252 offset:35840
	global_load_lds_dwordx4 v142, s[100:101]
	ds_read_b128 v[174:177], v252 offset:49152
	ds_read_b128 v[182:185], v252 offset:50176
	ds_read_b128 v[186:189], v252 offset:51200
	ds_read_b128 v[190:193], v252 offset:52224
	ds_read_b128 v[194:197], v161 offset:32768
	ds_read_b128 v[198:201], v161 offset:33792
	ds_read_b128 v[202:205], v161 offset:34816
	ds_read_b128 v[206:209], v161 offset:35840
	ds_read_b128 v[210:213], v161 offset:36864
	ds_read_b128 v[214:217], v161 offset:37888
	ds_read_b128 v[218:221], v161 offset:38912
	ds_read_b128 v[222:225], v161 offset:39936
	s_waitcnt vmcnt(9)
	s_mov_b32 m0, 0x21800
	s_mov_b64 exec, 0xfff
	s_waitcnt lgkmcnt(0)
	global_load_lds_dword v[242:243], off offset:128
	s_mov_b64 exec, -1
	s_barrier
	v_mfma_f32_16x16x32_bf16 v[126:129], v[152:155], v[194:197], v[126:129]
	v_mfma_f32_16x16x32_bf16 v[126:129], v[162:165], v[198:201], v[126:129]
	v_mfma_f32_16x16x32_bf16 v[122:125], v[166:169], v[194:197], v[122:125]
	v_mfma_f32_16x16x32_bf16 v[122:125], v[170:173], v[198:201], v[122:125]
	v_mfma_f32_16x16x32_bf16 v[110:113], v[152:155], v[202:205], v[110:113]
	v_mfma_f32_16x16x32_bf16 v[110:113], v[162:165], v[206:209], v[110:113]
	v_mfma_f32_16x16x32_bf16 v[106:109], v[166:169], v[202:205], v[106:109]
	v_mfma_f32_16x16x32_bf16 v[106:109], v[170:173], v[206:209], v[106:109]
	v_mfma_f32_16x16x32_bf16 v[94:97], v[152:155], v[210:213], v[94:97]
	v_mfma_f32_16x16x32_bf16 v[94:97], v[162:165], v[214:217], v[94:97]
	v_mfma_f32_16x16x32_bf16 v[90:93], v[166:169], v[210:213], v[90:93]
	v_mfma_f32_16x16x32_bf16 v[90:93], v[170:173], v[214:217], v[90:93]
	v_mfma_f32_16x16x32_bf16 v[78:81], v[152:155], v[218:221], v[78:81]
	v_mfma_f32_16x16x32_bf16 v[78:81], v[162:165], v[222:225], v[78:81]
	v_mfma_f32_16x16x32_bf16 v[74:77], v[166:169], v[218:221], v[74:77]
	v_mfma_f32_16x16x32_bf16 v[74:77], v[170:173], v[222:225], v[74:77]
	v_mfma_f32_16x16x32_bf16 v[118:121], v[174:177], v[194:197], v[118:121]
	v_mfma_f32_16x16x32_bf16 v[118:121], v[182:185], v[198:201], v[118:121]
	v_mfma_f32_16x16x32_bf16 v[114:117], v[186:189], v[194:197], v[114:117]
	v_mfma_f32_16x16x32_bf16 v[114:117], v[190:193], v[198:201], v[114:117]
	v_mfma_f32_16x16x32_bf16 v[102:105], v[174:177], v[202:205], v[102:105]
	v_mfma_f32_16x16x32_bf16 v[102:105], v[182:185], v[206:209], v[102:105]
	v_mfma_f32_16x16x32_bf16 v[98:101], v[186:189], v[202:205], v[98:101]
	v_mfma_f32_16x16x32_bf16 v[98:101], v[190:193], v[206:209], v[98:101]
	v_mfma_f32_16x16x32_bf16 v[86:89], v[174:177], v[210:213], v[86:89]
	v_mfma_f32_16x16x32_bf16 v[86:89], v[182:185], v[214:217], v[86:89]
	v_mfma_f32_16x16x32_bf16 v[82:85], v[186:189], v[210:213], v[82:85]
	v_mfma_f32_16x16x32_bf16 v[82:85], v[190:193], v[214:217], v[82:85]
	v_mfma_f32_16x16x32_bf16 v[70:73], v[174:177], v[218:221], v[70:73]
	v_mfma_f32_16x16x32_bf16 v[70:73], v[182:185], v[222:225], v[70:73]
	v_mfma_f32_16x16x32_bf16 v[66:69], v[186:189], v[218:221], v[66:69]
	v_mfma_f32_16x16x32_bf16 v[66:69], v[190:193], v[222:225], v[66:69]
	s_barrier
	s_add_u32 s14, s14, 0x80
	s_addc_u32 s15, s15, 0
	s_add_i32 m0, s28, 0x18000
	ds_read_b128 v[194:197], v161 offset:49152
	ds_read_b128 v[198:201], v161 offset:50176
	global_load_lds_dwordx4 v144, s[14:15]
	s_add_i32 m0, s28, 0x1a000
	s_add_u32 s98, s98, 0x80
	s_addc_u32 s99, s99, 0
	ds_read_b128 v[202:205], v161 offset:51200
	global_load_lds_dwordx4 v140, s[14:15]
	s_add_i32 m0, s28, 0x1c000
	ds_read_b128 v[206:209], v161 offset:52224
	ds_read_b128 v[210:213], v161 offset:53248
	global_load_lds_dwordx4 v144, s[98:99]
	s_add_i32 m0, s28, 0x1e000
	s_add_u32 s16, s16, 0x80
	s_addc_u32 s17, s17, 0
	ds_read_b128 v[214:217], v161 offset:54272
	ds_read_b128 v[218:221], v161 offset:55296
	global_load_lds_dwordx4 v140, s[98:99]
	s_mov_b32 m0, s45
	ds_read_b128 v[222:225], v161 offset:56320
	global_load_lds_dwordx4 v146, s[16:17]
	s_mov_b32 m0, s46
	s_nop 0
	global_load_lds_dwordx4 v142, s[16:17]
	s_waitcnt vmcnt(9)
	s_waitcnt lgkmcnt(0)
	s_barrier
	v_mfma_f32_16x16x32_bf16 v[62:65], v[152:155], v[194:197], v[62:65]
	v_mfma_f32_16x16x32_bf16 v[62:65], v[162:165], v[198:201], v[62:65]
	v_mfma_f32_16x16x32_bf16 v[58:61], v[166:169], v[194:197], v[58:61]
	v_mfma_f32_16x16x32_bf16 v[58:61], v[170:173], v[198:201], v[58:61]
	v_mfma_f32_16x16x32_bf16 v[46:49], v[152:155], v[202:205], v[46:49]
	v_mfma_f32_16x16x32_bf16 v[46:49], v[162:165], v[206:209], v[46:49]
	v_mfma_f32_16x16x32_bf16 v[42:45], v[166:169], v[202:205], v[42:45]
	v_mfma_f32_16x16x32_bf16 v[42:45], v[170:173], v[206:209], v[42:45]
	v_mfma_f32_16x16x32_bf16 v[30:33], v[152:155], v[210:213], v[30:33]
	v_mfma_f32_16x16x32_bf16 v[30:33], v[162:165], v[214:217], v[30:33]
	v_mfma_f32_16x16x32_bf16 v[26:29], v[166:169], v[210:213], v[26:29]
	v_mfma_f32_16x16x32_bf16 v[26:29], v[170:173], v[214:217], v[26:29]
	v_mfma_f32_16x16x32_bf16 v[14:17], v[152:155], v[218:221], v[14:17]
	v_mfma_f32_16x16x32_bf16 v[14:17], v[162:165], v[222:225], v[14:17]
	v_mfma_f32_16x16x32_bf16 v[10:13], v[166:169], v[218:221], v[10:13]
	v_mfma_f32_16x16x32_bf16 v[10:13], v[170:173], v[222:225], v[10:13]
	v_mfma_f32_16x16x32_bf16 v[54:57], v[174:177], v[194:197], v[54:57]
	v_mfma_f32_16x16x32_bf16 v[54:57], v[182:185], v[198:201], v[54:57]
	v_mfma_f32_16x16x32_bf16 v[50:53], v[186:189], v[194:197], v[50:53]
	v_mfma_f32_16x16x32_bf16 v[50:53], v[190:193], v[198:201], v[50:53]
	v_mfma_f32_16x16x32_bf16 v[38:41], v[174:177], v[202:205], v[38:41]
	v_mfma_f32_16x16x32_bf16 v[38:41], v[182:185], v[206:209], v[38:41]
	v_mfma_f32_16x16x32_bf16 v[34:37], v[186:189], v[202:205], v[34:37]
	v_mfma_f32_16x16x32_bf16 v[34:37], v[190:193], v[206:209], v[34:37]
	v_mfma_f32_16x16x32_bf16 v[22:25], v[174:177], v[210:213], v[22:25]
	v_mfma_f32_16x16x32_bf16 v[22:25], v[182:185], v[214:217], v[22:25]
	v_mfma_f32_16x16x32_bf16 v[18:21], v[186:189], v[210:213], v[18:21]
	v_mfma_f32_16x16x32_bf16 v[18:21], v[190:193], v[214:217], v[18:21]
	v_mfma_f32_16x16x32_bf16 v[6:9], v[174:177], v[218:221], v[6:9]
	v_mfma_f32_16x16x32_bf16 v[6:9], v[182:185], v[222:225], v[6:9]
	v_mfma_f32_16x16x32_bf16 v[2:5], v[186:189], v[218:221], v[2:5]
	v_mfma_f32_16x16x32_bf16 v[2:5], v[190:193], v[222:225], v[2:5]
	s_barrier
	s_add_i32 s39, s39, 2
	s_add_u32 s12, s12, 0x100
	s_addc_u32 s13, s13, 0
	s_add_u32 s0, s0, 0x100
	s_addc_u32 s1, s1, 0
	s_cmp_gt_u32 s39, 61
	s_cbranch_scc0 .LBB0_341
	s_and_b64 vcc, exec, s[34:35]
	s_cbranch_vccz .LBB0_344
	s_barrier

.LBB0_571:
	s_and_b32 s98, s47, 3
	s_and_b32 s99, s46, 7
	s_lshl_b32 s98, s98, 6
	s_lshl_b32 s99, s99, 5
	v_and_b32_e32 v244, 63, v0
	v_mul_u32_u24_e32 v245, 86, v244
	v_lshrrev_b32_e32 v245, 10, v245
	v_mul_u32_u24_e32 v245, 12, v245
	v_sub_u32_e32 v244, v244, v245
	v_lshrrev_b32_e32 v245, 6, v0
	v_mad_u32_u24 v244, v245, 12, v244
	v_cmp_gt_u32_e32 vcc, 64, v244
	v_add_u32_e32 v245, s98, v244
	v_subrev_u32_e32 v247, 64, v244
	v_add_u32_e32 v248, s99, v247
	v_cndmask_b32_e32 v245, v248, v245, vcc
	v_lshlrev_b32_e32 v245, 13, v245
	v_add_u32_e32 v244, 0x80, v245
	v_mov_b32_e32 v245, 0
	v_mov_b32_e32 v246, s12
	v_mov_b32_e32 v247, s13
	v_mov_b32_e32 v248, s14
	v_mov_b32_e32 v249, s15
	v_cndmask_b32_e32 v246, v248, v246, vcc
	v_cndmask_b32_e32 v247, v249, v247, vcc
	v_lshl_add_u64 v[242:243], v[246:247], 0, v[244:245]
	v_add_u32_e32 v252, 0x10000, v159
	s_add_u32 s12, s12, 0x100080
	s_addc_u32 s13, s13, 0
	s_add_u32 s0, s14, 0x100
	v_mov_b32_e32 v2, 0
	s_addc_u32 s1, s15, 0
	s_mov_b32 s35, -2
	v_mov_b32_e32 v3, v2
	v_mov_b32_e32 v4, v2
	v_mov_b32_e32 v5, v2
	v_mov_b32_e32 v6, v2
	v_mov_b32_e32 v7, v2
	v_mov_b32_e32 v8, v2
	v_mov_b32_e32 v9, v2
	v_mov_b32_e32 v18, v2
	v_mov_b32_e32 v19, v2
	v_mov_b32_e32 v20, v2
	v_mov_b32_e32 v21, v2
	v_mov_b32_e32 v22, v2
	v_mov_b32_e32 v23, v2
	v_mov_b32_e32 v24, v2
	v_mov_b32_e32 v25, v2
	v_mov_b32_e32 v34, v2
	v_mov_b32_e32 v35, v2
	v_mov_b32_e32 v36, v2
	v_mov_b32_e32 v37, v2
	v_mov_b32_e32 v38, v2
	v_mov_b32_e32 v39, v2
	v_mov_b32_e32 v40, v2
	v_mov_b32_e32 v41, v2
	v_mov_b32_e32 v50, v2
	v_mov_b32_e32 v51, v2
	v_mov_b32_e32 v52, v2
	v_mov_b32_e32 v53, v2
	v_mov_b32_e32 v54, v2
	v_mov_b32_e32 v55, v2
	v_mov_b32_e32 v56, v2
	v_mov_b32_e32 v57, v2
	v_mov_b32_e32 v10, v2
	v_mov_b32_e32 v11, v2
	v_mov_b32_e32 v12, v2
	v_mov_b32_e32 v13, v2
	v_mov_b32_e32 v14, v2
	v_mov_b32_e32 v15, v2
	v_mov_b32_e32 v16, v2
	v_mov_b32_e32 v17, v2
	v_mov_b32_e32 v26, v2
	v_mov_b32_e32 v27, v2
	v_mov_b32_e32 v28, v2
	v_mov_b32_e32 v29, v2
	v_mov_b32_e32 v30, v2
	v_mov_b32_e32 v31, v2
	v_mov_b32_e32 v32, v2
	v_mov_b32_e32 v33, v2
	v_mov_b32_e32 v42, v2
	v_mov_b32_e32 v43, v2
	v_mov_b32_e32 v44, v2
	v_mov_b32_e32 v45, v2
	v_mov_b32_e32 v46, v2
	v_mov_b32_e32 v47, v2
	v_mov_b32_e32 v48, v2
	v_mov_b32_e32 v49, v2
	v_mov_b32_e32 v58, v2
	v_mov_b32_e32 v59, v2
	v_mov_b32_e32 v60, v2
	v_mov_b32_e32 v61, v2
	v_mov_b32_e32 v62, v2
	v_mov_b32_e32 v63, v2
	v_mov_b32_e32 v64, v2
	v_mov_b32_e32 v65, v2
	v_mov_b32_e32 v66, v2
	v_mov_b32_e32 v67, v2
	v_mov_b32_e32 v68, v2
	v_mov_b32_e32 v69, v2
	v_mov_b32_e32 v70, v2
	v_mov_b32_e32 v71, v2
	v_mov_b32_e32 v72, v2
	v_mov_b32_e32 v73, v2
	v_mov_b32_e32 v82, v2
	v_mov_b32_e32 v83, v2
	v_mov_b32_e32 v84, v2
	v_mov_b32_e32 v85, v2
	v_mov_b32_e32 v86, v2
	v_mov_b32_e32 v87, v2
	v_mov_b32_e32 v88, v2
	v_mov_b32_e32 v89, v2
	v_mov_b32_e32 v98, v2
	v_mov_b32_e32 v99, v2
	v_mov_b32_e32 v100, v2
	v_mov_b32_e32 v101, v2
	v_mov_b32_e32 v102, v2
	v_mov_b32_e32 v103, v2
	v_mov_b32_e32 v104, v2
	v_mov_b32_e32 v105, v2
	v_mov_b32_e32 v114, v2
	v_mov_b32_e32 v115, v2
	v_mov_b32_e32 v116, v2
	v_mov_b32_e32 v117, v2
	v_mov_b32_e32 v118, v2
	v_mov_b32_e32 v119, v2
	v_mov_b32_e32 v120, v2
	v_mov_b32_e32 v121, v2
	v_mov_b32_e32 v74, v2
	v_mov_b32_e32 v75, v2
	v_mov_b32_e32 v76, v2
	v_mov_b32_e32 v77, v2
	v_mov_b32_e32 v78, v2
	v_mov_b32_e32 v79, v2
	v_mov_b32_e32 v80, v2
	v_mov_b32_e32 v81, v2
	v_mov_b32_e32 v90, v2
	v_mov_b32_e32 v91, v2
	v_mov_b32_e32 v92, v2
	v_mov_b32_e32 v93, v2
	v_mov_b32_e32 v94, v2
	v_mov_b32_e32 v95, v2
	v_mov_b32_e32 v96, v2
	v_mov_b32_e32 v97, v2
	v_mov_b32_e32 v106, v2
	v_mov_b32_e32 v107, v2
	v_mov_b32_e32 v108, v2
	v_mov_b32_e32 v109, v2
	v_mov_b32_e32 v110, v2
	v_mov_b32_e32 v111, v2
	v_mov_b32_e32 v112, v2
	v_mov_b32_e32 v113, v2
	v_mov_b32_e32 v122, v2
	v_mov_b32_e32 v123, v2
	v_mov_b32_e32 v124, v2
	v_mov_b32_e32 v125, v2
	v_mov_b32_e32 v126, v2
	v_mov_b32_e32 v127, v2
	v_mov_b32_e32 v128, v2
	v_mov_b32_e32 v129, v2
.LBB0_572:
	s_add_u32 s14, s12, 0xfff00080
	s_addc_u32 s15, s13, -1
	s_cmp_eq_u32 s35, 60
	s_cselect_b32 s17, s51, s15
	s_cselect_b32 s16, s50, s14
	s_cselect_b32 s15, s53, s1
	s_cselect_b32 s14, s52, s0
	s_cmp_lt_i32 s35, 58
	s_cselect_b32 s100, 0x100, 0
	s_mov_b32 s101, 0
	v_lshl_add_u64 v[242:243], v[242:243], 0, s[100:101]
	s_add_i32 m0, s8, 0xc000
	ds_read_b128 v[152:155], v252
	ds_read_b128 v[162:165], v252 offset:1024
	global_load_lds_dwordx4 v148, s[12:13]
	s_add_i32 m0, s8, 0xe000
	ds_read_b128 v[166:169], v252 offset:2048
	ds_read_b128 v[170:173], v252 offset:3072
	global_load_lds_dwordx4 v150, s[12:13]
	ds_read_b128 v[174:177], v252 offset:16384
	ds_read_b128 v[182:185], v252 offset:17408
	ds_read_b128 v[186:189], v252 offset:18432
	ds_read_b128 v[190:193], v252 offset:19456
	ds_read_b128 v[194:197], v161
	ds_read_b128 v[198:201], v161 offset:1024
	ds_read_b128 v[202:205], v161 offset:2048
	ds_read_b128 v[206:209], v161 offset:3072
	ds_read_b128 v[210:213], v161 offset:4096
	ds_read_b128 v[214:217], v161 offset:5120
	ds_read_b128 v[218:221], v161 offset:6144
	ds_read_b128 v[222:225], v161 offset:7168
	s_waitcnt vmcnt(9)
	s_mov_b32 m0, 0x21800
	s_mov_b64 exec, 0xfff
	s_waitcnt lgkmcnt(0)
	global_load_lds_dword v[242:243], off
	s_mov_b64 exec, -1
	s_barrier
	v_mfma_f32_16x16x32_bf16 v[126:129], v[152:155], v[194:197], v[126:129]
	v_mfma_f32_16x16x32_bf16 v[126:129], v[162:165], v[198:201], v[126:129]
	v_mfma_f32_16x16x32_bf16 v[122:125], v[166:169], v[194:197], v[122:125]
	v_mfma_f32_16x16x32_bf16 v[122:125], v[170:173], v[198:201], v[122:125]
	v_mfma_f32_16x16x32_bf16 v[110:113], v[152:155], v[202:205], v[110:113]
	v_mfma_f32_16x16x32_bf16 v[110:113], v[162:165], v[206:209], v[110:113]
	v_mfma_f32_16x16x32_bf16 v[106:109], v[166:169], v[202:205], v[106:109]
	v_mfma_f32_16x16x32_bf16 v[106:109], v[170:173], v[206:209], v[106:109]
	v_mfma_f32_16x16x32_bf16 v[94:97], v[152:155], v[210:213], v[94:97]
	v_mfma_f32_16x16x32_bf16 v[94:97], v[162:165], v[214:217], v[94:97]
	v_mfma_f32_16x16x32_bf16 v[90:93], v[166:169], v[210:213], v[90:93]
	v_mfma_f32_16x16x32_bf16 v[90:93], v[170:173], v[214:217], v[90:93]
	v_mfma_f32_16x16x32_bf16 v[78:81], v[152:155], v[218:221], v[78:81]
	v_mfma_f32_16x16x32_bf16 v[78:81], v[162:165], v[222:225], v[78:81]
	v_mfma_f32_16x16x32_bf16 v[74:77], v[166:169], v[218:221], v[74:77]
	v_mfma_f32_16x16x32_bf16 v[74:77], v[170:173], v[222:225], v[74:77]
	v_mfma_f32_16x16x32_bf16 v[118:121], v[174:177], v[194:197], v[118:121]
	v_mfma_f32_16x16x32_bf16 v[118:121], v[182:185], v[198:201], v[118:121]
	v_mfma_f32_16x16x32_bf16 v[114:117], v[186:189], v[194:197], v[114:117]
	v_mfma_f32_16x16x32_bf16 v[114:117], v[190:193], v[198:201], v[114:117]
	v_mfma_f32_16x16x32_bf16 v[102:105], v[174:177], v[202:205], v[102:105]
	v_mfma_f32_16x16x32_bf16 v[102:105], v[182:185], v[206:209], v[102:105]
	v_mfma_f32_16x16x32_bf16 v[98:101], v[186:189], v[202:205], v[98:101]
	v_mfma_f32_16x16x32_bf16 v[98:101], v[190:193], v[206:209], v[98:101]
	v_mfma_f32_16x16x32_bf16 v[86:89], v[174:177], v[210:213], v[86:89]
	v_mfma_f32_16x16x32_bf16 v[86:89], v[182:185], v[214:217], v[86:89]
	v_mfma_f32_16x16x32_bf16 v[82:85], v[186:189], v[210:213], v[82:85]
	v_mfma_f32_16x16x32_bf16 v[82:85], v[190:193], v[214:217], v[82:85]
	v_mfma_f32_16x16x32_bf16 v[70:73], v[174:177], v[218:221], v[70:73]
	v_mfma_f32_16x16x32_bf16 v[70:73], v[182:185], v[222:225], v[70:73]
	v_mfma_f32_16x16x32_bf16 v[66:69], v[186:189], v[218:221], v[66:69]
	v_mfma_f32_16x16x32_bf16 v[66:69], v[190:193], v[222:225], v[66:69]
	s_barrier
	s_add_i32 m0, s28, 0x10000
	ds_read_b128 v[194:197], v161 offset:16384
	ds_read_b128 v[198:201], v161 offset:17408
	global_load_lds_dwordx4 v144, s[14:15]
	s_add_i32 m0, s28, 0x12000
	s_add_u32 s98, s14, 0x100000
	s_addc_u32 s99, s15, 0
	ds_read_b128 v[202:205], v161 offset:18432
	global_load_lds_dwordx4 v140, s[14:15]
	s_add_i32 m0, s28, 0x14000
	ds_read_b128 v[206:209], v161 offset:19456
	ds_read_b128 v[210:213], v161 offset:20480
	global_load_lds_dwordx4 v144, s[98:99]
	s_add_i32 m0, s28, 0x16000
	ds_read_b128 v[214:217], v161 offset:21504
	ds_read_b128 v[218:221], v161 offset:22528
	global_load_lds_dwordx4 v140, s[98:99]
	s_mov_b32 m0, s8
	ds_read_b128 v[222:225], v161 offset:23552
	global_load_lds_dwordx4 v146, s[16:17]
	s_mov_b32 m0, s9
	s_nop 0
	global_load_lds_dwordx4 v142, s[16:17]
	s_waitcnt vmcnt(9)
	s_waitcnt lgkmcnt(0)
	s_barrier
	v_mfma_f32_16x16x32_bf16 v[62:65], v[152:155], v[194:197], v[62:65]
	v_mfma_f32_16x16x32_bf16 v[62:65], v[162:165], v[198:201], v[62:65]
	v_mfma_f32_16x16x32_bf16 v[58:61], v[166:169], v[194:197], v[58:61]
	v_mfma_f32_16x16x32_bf16 v[58:61], v[170:173], v[198:201], v[58:61]
	v_mfma_f32_16x16x32_bf16 v[46:49], v[152:155], v[202:205], v[46:49]
	v_mfma_f32_16x16x32_bf16 v[46:49], v[162:165], v[206:209], v[46:49]
	v_mfma_f32_16x16x32_bf16 v[42:45], v[166:169], v[202:205], v[42:45]
	v_mfma_f32_16x16x32_bf16 v[42:45], v[170:173], v[206:209], v[42:45]
	v_mfma_f32_16x16x32_bf16 v[30:33], v[152:155], v[210:213], v[30:33]
	v_mfma_f32_16x16x32_bf16 v[30:33], v[162:165], v[214:217], v[30:33]
	v_mfma_f32_16x16x32_bf16 v[26:29], v[166:169], v[210:213], v[26:29]
	v_mfma_f32_16x16x32_bf16 v[26:29], v[170:173], v[214:217], v[26:29]
	v_mfma_f32_16x16x32_bf16 v[14:17], v[152:155], v[218:221], v[14:17]
	v_mfma_f32_16x16x32_bf16 v[14:17], v[162:165], v[222:225], v[14:17]
	v_mfma_f32_16x16x32_bf16 v[10:13], v[166:169], v[218:221], v[10:13]
	v_mfma_f32_16x16x32_bf16 v[10:13], v[170:173], v[222:225], v[10:13]
	v_mfma_f32_16x16x32_bf16 v[54:57], v[174:177], v[194:197], v[54:57]
	v_mfma_f32_16x16x32_bf16 v[54:57], v[182:185], v[198:201], v[54:57]
	v_mfma_f32_16x16x32_bf16 v[50:53], v[186:189], v[194:197], v[50:53]
	v_mfma_f32_16x16x32_bf16 v[50:53], v[190:193], v[198:201], v[50:53]
	v_mfma_f32_16x16x32_bf16 v[38:41], v[174:177], v[202:205], v[38:41]
	v_mfma_f32_16x16x32_bf16 v[38:41], v[182:185], v[206:209], v[38:41]
	v_mfma_f32_16x16x32_bf16 v[34:37], v[186:189], v[202:205], v[34:37]
	v_mfma_f32_16x16x32_bf16 v[34:37], v[190:193], v[206:209], v[34:37]
	v_mfma_f32_16x16x32_bf16 v[22:25], v[174:177], v[210:213], v[22:25]
	v_mfma_f32_16x16x32_bf16 v[22:25], v[182:185], v[214:217], v[22:25]
	v_mfma_f32_16x16x32_bf16 v[18:21], v[186:189], v[210:213], v[18:21]
	v_mfma_f32_16x16x32_bf16 v[18:21], v[190:193], v[214:217], v[18:21]
	v_mfma_f32_16x16x32_bf16 v[6:9], v[174:177], v[218:221], v[6:9]
	v_mfma_f32_16x16x32_bf16 v[6:9], v[182:185], v[222:225], v[6:9]
	v_mfma_f32_16x16x32_bf16 v[2:5], v[186:189], v[218:221], v[2:5]
	v_mfma_f32_16x16x32_bf16 v[2:5], v[190:193], v[222:225], v[2:5]
	s_barrier
	s_add_u32 s100, s16, 0x100000
	s_addc_u32 s101, s17, 0
	s_mov_b32 m0, s29
	ds_read_b128 v[152:155], v252 offset:32768
	ds_read_b128 v[162:165], v252 offset:33792
	global_load_lds_dwordx4 v146, s[100:101]
	s_mov_b32 m0, s36
	ds_read_b128 v[166:169], v252 offset:34816
	ds_read_b128 v[170:173], v252 offset:35840
	global_load_lds_dwordx4 v142, s[100:101]
	ds_read_b128 v[174:177], v252 offset:49152
	ds_read_b128 v[182:185], v252 offset:50176
	ds_read_b128 v[186:189], v252 offset:51200
	ds_read_b128 v[190:193], v252 offset:52224
	ds_read_b128 v[194:197], v161 offset:32768
	ds_read_b128 v[198:201], v161 offset:33792
	ds_read_b128 v[202:205], v161 offset:34816
	ds_read_b128 v[206:209], v161 offset:35840
	ds_read_b128 v[210:213], v161 offset:36864
	ds_read_b128 v[214:217], v161 offset:37888
	ds_read_b128 v[218:221], v161 offset:38912
	ds_read_b128 v[222:225], v161 offset:39936
	s_waitcnt vmcnt(9)
	s_mov_b32 m0, 0x21800
	s_mov_b64 exec, 0xfff
	s_waitcnt lgkmcnt(0)
	global_load_lds_dword v[242:243], off offset:128
	s_mov_b64 exec, -1
	s_barrier
	v_mfma_f32_16x16x32_bf16 v[126:129], v[152:155], v[194:197], v[126:129]
	v_mfma_f32_16x16x32_bf16 v[126:129], v[162:165], v[198:201], v[126:129]
	v_mfma_f32_16x16x32_bf16 v[122:125], v[166:169], v[194:197], v[122:125]
	v_mfma_f32_16x16x32_bf16 v[122:125], v[170:173], v[198:201], v[122:125]
	v_mfma_f32_16x16x32_bf16 v[110:113], v[152:155], v[202:205], v[110:113]
	v_mfma_f32_16x16x32_bf16 v[110:113], v[162:165], v[206:209], v[110:113]
	v_mfma_f32_16x16x32_bf16 v[106:109], v[166:169], v[202:205], v[106:109]
	v_mfma_f32_16x16x32_bf16 v[106:109], v[170:173], v[206:209], v[106:109]
	v_mfma_f32_16x16x32_bf16 v[94:97], v[152:155], v[210:213], v[94:97]
	v_mfma_f32_16x16x32_bf16 v[94:97], v[162:165], v[214:217], v[94:97]
	v_mfma_f32_16x16x32_bf16 v[90:93], v[166:169], v[210:213], v[90:93]
	v_mfma_f32_16x16x32_bf16 v[90:93], v[170:173], v[214:217], v[90:93]
	v_mfma_f32_16x16x32_bf16 v[78:81], v[152:155], v[218:221], v[78:81]
	v_mfma_f32_16x16x32_bf16 v[78:81], v[162:165], v[222:225], v[78:81]
	v_mfma_f32_16x16x32_bf16 v[74:77], v[166:169], v[218:221], v[74:77]
	v_mfma_f32_16x16x32_bf16 v[74:77], v[170:173], v[222:225], v[74:77]
	v_mfma_f32_16x16x32_bf16 v[118:121], v[174:177], v[194:197], v[118:121]
	v_mfma_f32_16x16x32_bf16 v[118:121], v[182:185], v[198:201], v[118:121]
	v_mfma_f32_16x16x32_bf16 v[114:117], v[186:189], v[194:197], v[114:117]
	v_mfma_f32_16x16x32_bf16 v[114:117], v[190:193], v[198:201], v[114:117]
	v_mfma_f32_16x16x32_bf16 v[102:105], v[174:177], v[202:205], v[102:105]
	v_mfma_f32_16x16x32_bf16 v[102:105], v[182:185], v[206:209], v[102:105]
	v_mfma_f32_16x16x32_bf16 v[98:101], v[186:189], v[202:205], v[98:101]
	v_mfma_f32_16x16x32_bf16 v[98:101], v[190:193], v[206:209], v[98:101]
	v_mfma_f32_16x16x32_bf16 v[86:89], v[174:177], v[210:213], v[86:89]
	v_mfma_f32_16x16x32_bf16 v[86:89], v[182:185], v[214:217], v[86:89]
	v_mfma_f32_16x16x32_bf16 v[82:85], v[186:189], v[210:213], v[82:85]
	v_mfma_f32_16x16x32_bf16 v[82:85], v[190:193], v[214:217], v[82:85]
	v_mfma_f32_16x16x32_bf16 v[70:73], v[174:177], v[218:221], v[70:73]
	v_mfma_f32_16x16x32_bf16 v[70:73], v[182:185], v[222:225], v[70:73]
	v_mfma_f32_16x16x32_bf16 v[66:69], v[186:189], v[218:221], v[66:69]
	v_mfma_f32_16x16x32_bf16 v[66:69], v[190:193], v[222:225], v[66:69]
	s_barrier
	s_add_u32 s14, s14, 0x80
	s_addc_u32 s15, s15, 0
	s_add_i32 m0, s28, 0x18000
	ds_read_b128 v[194:197], v161 offset:49152
	ds_read_b128 v[198:201], v161 offset:50176
	global_load_lds_dwordx4 v144, s[14:15]
	s_add_i32 m0, s28, 0x1a000
	s_add_u32 s98, s98, 0x80
	s_addc_u32 s99, s99, 0
	ds_read_b128 v[202:205], v161 offset:51200
	global_load_lds_dwordx4 v140, s[14:15]
	s_add_i32 m0, s28, 0x1c000
	ds_read_b128 v[206:209], v161 offset:52224
	ds_read_b128 v[210:213], v161 offset:53248
	global_load_lds_dwordx4 v144, s[98:99]
	s_add_i32 m0, s28, 0x1e000
	s_add_u32 s16, s16, 0x80
	s_addc_u32 s17, s17, 0
	ds_read_b128 v[214:217], v161 offset:54272
	ds_read_b128 v[218:221], v161 offset:55296
	global_load_lds_dwordx4 v140, s[98:99]
	s_mov_b32 m0, s39
	ds_read_b128 v[222:225], v161 offset:56320
	global_load_lds_dwordx4 v146, s[16:17]
	s_mov_b32 m0, s44
	s_nop 0
	global_load_lds_dwordx4 v142, s[16:17]
	s_waitcnt vmcnt(9)
	s_waitcnt lgkmcnt(0)
	s_barrier
	v_mfma_f32_16x16x32_bf16 v[62:65], v[152:155], v[194:197], v[62:65]
	v_mfma_f32_16x16x32_bf16 v[62:65], v[162:165], v[198:201], v[62:65]
	v_mfma_f32_16x16x32_bf16 v[58:61], v[166:169], v[194:197], v[58:61]
	v_mfma_f32_16x16x32_bf16 v[58:61], v[170:173], v[198:201], v[58:61]
	v_mfma_f32_16x16x32_bf16 v[46:49], v[152:155], v[202:205], v[46:49]
	v_mfma_f32_16x16x32_bf16 v[46:49], v[162:165], v[206:209], v[46:49]
	v_mfma_f32_16x16x32_bf16 v[42:45], v[166:169], v[202:205], v[42:45]
	v_mfma_f32_16x16x32_bf16 v[42:45], v[170:173], v[206:209], v[42:45]
	v_mfma_f32_16x16x32_bf16 v[30:33], v[152:155], v[210:213], v[30:33]
	v_mfma_f32_16x16x32_bf16 v[30:33], v[162:165], v[214:217], v[30:33]
	v_mfma_f32_16x16x32_bf16 v[26:29], v[166:169], v[210:213], v[26:29]
	v_mfma_f32_16x16x32_bf16 v[26:29], v[170:173], v[214:217], v[26:29]
	v_mfma_f32_16x16x32_bf16 v[14:17], v[152:155], v[218:221], v[14:17]
	v_mfma_f32_16x16x32_bf16 v[14:17], v[162:165], v[222:225], v[14:17]
	v_mfma_f32_16x16x32_bf16 v[10:13], v[166:169], v[218:221], v[10:13]
	v_mfma_f32_16x16x32_bf16 v[10:13], v[170:173], v[222:225], v[10:13]
	v_mfma_f32_16x16x32_bf16 v[54:57], v[174:177], v[194:197], v[54:57]
	v_mfma_f32_16x16x32_bf16 v[54:57], v[182:185], v[198:201], v[54:57]
	v_mfma_f32_16x16x32_bf16 v[50:53], v[186:189], v[194:197], v[50:53]
	v_mfma_f32_16x16x32_bf16 v[50:53], v[190:193], v[198:201], v[50:53]
	v_mfma_f32_16x16x32_bf16 v[38:41], v[174:177], v[202:205], v[38:41]
	v_mfma_f32_16x16x32_bf16 v[38:41], v[182:185], v[206:209], v[38:41]
	v_mfma_f32_16x16x32_bf16 v[34:37], v[186:189], v[202:205], v[34:37]
	v_mfma_f32_16x16x32_bf16 v[34:37], v[190:193], v[206:209], v[34:37]
	v_mfma_f32_16x16x32_bf16 v[22:25], v[174:177], v[210:213], v[22:25]
	v_mfma_f32_16x16x32_bf16 v[22:25], v[182:185], v[214:217], v[22:25]
	v_mfma_f32_16x16x32_bf16 v[18:21], v[186:189], v[210:213], v[18:21]
	v_mfma_f32_16x16x32_bf16 v[18:21], v[190:193], v[214:217], v[18:21]
	v_mfma_f32_16x16x32_bf16 v[6:9], v[174:177], v[218:221], v[6:9]
	v_mfma_f32_16x16x32_bf16 v[6:9], v[182:185], v[222:225], v[6:9]
	v_mfma_f32_16x16x32_bf16 v[2:5], v[186:189], v[218:221], v[2:5]
	v_mfma_f32_16x16x32_bf16 v[2:5], v[190:193], v[222:225], v[2:5]
	s_barrier
	s_add_i32 s35, s35, 2
	s_add_u32 s12, s12, 0x100
	s_addc_u32 s13, s13, 0
	s_add_u32 s0, s0, 0x100
	s_addc_u32 s1, s1, 0
	s_cmp_gt_u32 s35, 61
	s_cbranch_scc0 .LBB0_572
	s_and_b64 vcc, exec, s[10:11]
	s_cbranch_vccz .LBB0_575
	s_barrier

.LBB0_881:
	s_and_b32 s98, s30, 3
	s_and_b32 s99, s28, 7
	s_lshl_b32 s98, s98, 6
	s_lshl_b32 s99, s99, 5
	v_and_b32_e32 v244, 63, v0
	v_mul_u32_u24_e32 v245, 86, v244
	v_lshrrev_b32_e32 v245, 10, v245
	v_mul_u32_u24_e32 v245, 12, v245
	v_sub_u32_e32 v244, v244, v245
	v_lshrrev_b32_e32 v245, 6, v0
	v_mad_u32_u24 v244, v245, 12, v244
	v_cmp_gt_u32_e32 vcc, 64, v244
	v_add_u32_e32 v245, s98, v244
	v_subrev_u32_e32 v247, 64, v244
	v_add_u32_e32 v248, s99, v247
	v_cndmask_b32_e32 v245, v248, v245, vcc
	v_lshlrev_b32_e32 v245, 13, v245
	v_add_u32_e32 v244, 0x80, v245
	v_mov_b32_e32 v245, 0
	v_mov_b32_e32 v246, s10
	v_mov_b32_e32 v247, s11
	v_mov_b32_e32 v248, s38
	v_mov_b32_e32 v249, s39
	v_cndmask_b32_e32 v246, v248, v246, vcc
	v_cndmask_b32_e32 v247, v249, v247, vcc
	v_lshl_add_u64 v[242:243], v[246:247], 0, v[244:245]
	v_add_u32_e32 v252, 0x10000, v155
	s_add_u32 s10, s10, 0x100080
	s_addc_u32 s11, s11, 0
	s_add_u32 s0, s38, 0x100
	v_mov_b32_e32 v4, 0
	s_addc_u32 s1, s39, 0
	s_mov_b32 s12, -2
	v_mov_b32_e32 v5, v4
	v_mov_b32_e32 v6, v4
	v_mov_b32_e32 v7, v4
	v_mov_b32_e32 v8, v4
	v_mov_b32_e32 v9, v4
	v_mov_b32_e32 v10, v4
	v_mov_b32_e32 v11, v4
	v_mov_b32_e32 v20, v4
	v_mov_b32_e32 v21, v4
	v_mov_b32_e32 v22, v4
	v_mov_b32_e32 v23, v4
	v_mov_b32_e32 v24, v4
	v_mov_b32_e32 v25, v4
	v_mov_b32_e32 v26, v4
	v_mov_b32_e32 v27, v4
	v_mov_b32_e32 v36, v4
	v_mov_b32_e32 v37, v4
	v_mov_b32_e32 v38, v4
	v_mov_b32_e32 v39, v4
	v_mov_b32_e32 v40, v4
	v_mov_b32_e32 v41, v4
	v_mov_b32_e32 v42, v4
	v_mov_b32_e32 v43, v4
	v_mov_b32_e32 v52, v4
	v_mov_b32_e32 v53, v4
	v_mov_b32_e32 v54, v4
	v_mov_b32_e32 v55, v4
	v_mov_b32_e32 v56, v4
	v_mov_b32_e32 v57, v4
	v_mov_b32_e32 v58, v4
	v_mov_b32_e32 v59, v4
	v_mov_b32_e32 v12, v4
	v_mov_b32_e32 v13, v4
	v_mov_b32_e32 v14, v4
	v_mov_b32_e32 v15, v4
	v_mov_b32_e32 v16, v4
	v_mov_b32_e32 v17, v4
	v_mov_b32_e32 v18, v4
	v_mov_b32_e32 v19, v4
	v_mov_b32_e32 v28, v4
	v_mov_b32_e32 v29, v4
	v_mov_b32_e32 v30, v4
	v_mov_b32_e32 v31, v4
	v_mov_b32_e32 v32, v4
	v_mov_b32_e32 v33, v4
	v_mov_b32_e32 v34, v4
	v_mov_b32_e32 v35, v4
	v_mov_b32_e32 v44, v4
	v_mov_b32_e32 v45, v4
	v_mov_b32_e32 v46, v4
	v_mov_b32_e32 v47, v4
	v_mov_b32_e32 v48, v4
	v_mov_b32_e32 v49, v4
	v_mov_b32_e32 v50, v4
	v_mov_b32_e32 v51, v4
	v_mov_b32_e32 v60, v4
	v_mov_b32_e32 v61, v4
	v_mov_b32_e32 v62, v4
	v_mov_b32_e32 v63, v4
	v_mov_b32_e32 v64, v4
	v_mov_b32_e32 v65, v4
	v_mov_b32_e32 v66, v4
	v_mov_b32_e32 v67, v4
	v_mov_b32_e32 v68, v4
	v_mov_b32_e32 v69, v4
	v_mov_b32_e32 v70, v4
	v_mov_b32_e32 v71, v4
	v_mov_b32_e32 v72, v4
	v_mov_b32_e32 v73, v4
	v_mov_b32_e32 v74, v4
	v_mov_b32_e32 v75, v4
	v_mov_b32_e32 v84, v4
	v_mov_b32_e32 v85, v4
	v_mov_b32_e32 v86, v4
	v_mov_b32_e32 v87, v4
	v_mov_b32_e32 v88, v4
	v_mov_b32_e32 v89, v4
	v_mov_b32_e32 v90, v4
	v_mov_b32_e32 v91, v4
	v_mov_b32_e32 v100, v4
	v_mov_b32_e32 v101, v4
	v_mov_b32_e32 v102, v4
	v_mov_b32_e32 v103, v4
	v_mov_b32_e32 v104, v4
	v_mov_b32_e32 v105, v4
	v_mov_b32_e32 v106, v4
	v_mov_b32_e32 v107, v4
	v_mov_b32_e32 v116, v4
	v_mov_b32_e32 v117, v4
	v_mov_b32_e32 v118, v4
	v_mov_b32_e32 v119, v4
	v_mov_b32_e32 v120, v4
	v_mov_b32_e32 v121, v4
	v_mov_b32_e32 v122, v4
	v_mov_b32_e32 v123, v4
	v_mov_b32_e32 v76, v4
	v_mov_b32_e32 v77, v4
	v_mov_b32_e32 v78, v4
	v_mov_b32_e32 v79, v4
	v_mov_b32_e32 v80, v4
	v_mov_b32_e32 v81, v4
	v_mov_b32_e32 v82, v4
	v_mov_b32_e32 v83, v4
	v_mov_b32_e32 v92, v4
	v_mov_b32_e32 v93, v4
	v_mov_b32_e32 v94, v4
	v_mov_b32_e32 v95, v4
	v_mov_b32_e32 v96, v4
	v_mov_b32_e32 v97, v4
	v_mov_b32_e32 v98, v4
	v_mov_b32_e32 v99, v4
	v_mov_b32_e32 v108, v4
	v_mov_b32_e32 v109, v4
	v_mov_b32_e32 v110, v4
	v_mov_b32_e32 v111, v4
	v_mov_b32_e32 v112, v4
	v_mov_b32_e32 v113, v4
	v_mov_b32_e32 v114, v4
	v_mov_b32_e32 v115, v4
	v_mov_b32_e32 v124, v4
	v_mov_b32_e32 v125, v4
	v_mov_b32_e32 v126, v4
	v_mov_b32_e32 v127, v4
	v_mov_b32_e32 v128, v4
	v_mov_b32_e32 v129, v4
	v_mov_b32_e32 v130, v4
	v_mov_b32_e32 v131, v4
.LBB0_882:
	s_add_u32 s20, s10, 0xfff00080
	s_addc_u32 s21, s11, -1
	s_cmp_eq_u32 s12, 60
	s_cselect_b32 s43, s55, s21
	s_cselect_b32 s42, s54, s20
	s_cselect_b32 s39, s37, s1
	s_cselect_b32 s38, s36, s0
	s_cmp_lt_i32 s12, 58
	s_cselect_b32 s100, 0x100, 0
	s_mov_b32 s101, 0
	v_lshl_add_u64 v[242:243], v[242:243], 0, s[100:101]
	s_add_i32 m0, s29, 0xc000
	ds_read_b128 v[146:149], v252
	ds_read_b128 v[150:153], v252 offset:1024
	global_load_lds_dwordx4 v140, s[10:11]
	s_add_i32 m0, s29, 0xe000
	ds_read_b128 v[158:161], v252 offset:2048
	ds_read_b128 v[162:165], v252 offset:3072
	global_load_lds_dwordx4 v142, s[10:11]
	ds_read_b128 v[166:169], v252 offset:16384
	ds_read_b128 v[170:173], v252 offset:17408
	ds_read_b128 v[174:177], v252 offset:18432
	ds_read_b128 v[186:189], v252 offset:19456
	ds_read_b128 v[190:193], v157
	ds_read_b128 v[194:197], v157 offset:1024
	ds_read_b128 v[198:201], v157 offset:2048
	ds_read_b128 v[202:205], v157 offset:3072
	ds_read_b128 v[206:209], v157 offset:4096
	ds_read_b128 v[210:213], v157 offset:5120
	ds_read_b128 v[214:217], v157 offset:6144
	ds_read_b128 v[218:221], v157 offset:7168
	s_waitcnt vmcnt(9)
	s_mov_b32 m0, 0x21800
	s_mov_b64 exec, 0xfff
	s_waitcnt lgkmcnt(0)
	global_load_lds_dword v[242:243], off
	s_mov_b64 exec, -1
	s_barrier
	v_mfma_f32_16x16x32_bf16 v[128:131], v[146:149], v[190:193], v[128:131]
	v_mfma_f32_16x16x32_bf16 v[128:131], v[150:153], v[194:197], v[128:131]
	v_mfma_f32_16x16x32_bf16 v[124:127], v[158:161], v[190:193], v[124:127]
	v_mfma_f32_16x16x32_bf16 v[124:127], v[162:165], v[194:197], v[124:127]
	v_mfma_f32_16x16x32_bf16 v[112:115], v[146:149], v[198:201], v[112:115]
	v_mfma_f32_16x16x32_bf16 v[112:115], v[150:153], v[202:205], v[112:115]
	v_mfma_f32_16x16x32_bf16 v[108:111], v[158:161], v[198:201], v[108:111]
	v_mfma_f32_16x16x32_bf16 v[108:111], v[162:165], v[202:205], v[108:111]
	v_mfma_f32_16x16x32_bf16 v[96:99], v[146:149], v[206:209], v[96:99]
	v_mfma_f32_16x16x32_bf16 v[96:99], v[150:153], v[210:213], v[96:99]
	v_mfma_f32_16x16x32_bf16 v[92:95], v[158:161], v[206:209], v[92:95]
	v_mfma_f32_16x16x32_bf16 v[92:95], v[162:165], v[210:213], v[92:95]
	v_mfma_f32_16x16x32_bf16 v[80:83], v[146:149], v[214:217], v[80:83]
	v_mfma_f32_16x16x32_bf16 v[80:83], v[150:153], v[218:221], v[80:83]
	v_mfma_f32_16x16x32_bf16 v[76:79], v[158:161], v[214:217], v[76:79]
	v_mfma_f32_16x16x32_bf16 v[76:79], v[162:165], v[218:221], v[76:79]
	v_mfma_f32_16x16x32_bf16 v[120:123], v[166:169], v[190:193], v[120:123]
	v_mfma_f32_16x16x32_bf16 v[120:123], v[170:173], v[194:197], v[120:123]
	v_mfma_f32_16x16x32_bf16 v[116:119], v[174:177], v[190:193], v[116:119]
	v_mfma_f32_16x16x32_bf16 v[116:119], v[186:189], v[194:197], v[116:119]
	v_mfma_f32_16x16x32_bf16 v[104:107], v[166:169], v[198:201], v[104:107]
	v_mfma_f32_16x16x32_bf16 v[104:107], v[170:173], v[202:205], v[104:107]
	v_mfma_f32_16x16x32_bf16 v[100:103], v[174:177], v[198:201], v[100:103]
	v_mfma_f32_16x16x32_bf16 v[100:103], v[186:189], v[202:205], v[100:103]
	v_mfma_f32_16x16x32_bf16 v[88:91], v[166:169], v[206:209], v[88:91]
	v_mfma_f32_16x16x32_bf16 v[88:91], v[170:173], v[210:213], v[88:91]
	v_mfma_f32_16x16x32_bf16 v[84:87], v[174:177], v[206:209], v[84:87]
	v_mfma_f32_16x16x32_bf16 v[84:87], v[186:189], v[210:213], v[84:87]
	v_mfma_f32_16x16x32_bf16 v[72:75], v[166:169], v[214:217], v[72:75]
	v_mfma_f32_16x16x32_bf16 v[72:75], v[170:173], v[218:221], v[72:75]
	v_mfma_f32_16x16x32_bf16 v[68:71], v[174:177], v[214:217], v[68:71]
	v_mfma_f32_16x16x32_bf16 v[68:71], v[186:189], v[218:221], v[68:71]
	s_barrier
	s_add_i32 m0, s58, 0x10000
	ds_read_b128 v[190:193], v157 offset:16384
	ds_read_b128 v[194:197], v157 offset:17408
	global_load_lds_dwordx4 v134, s[38:39]
	s_add_i32 m0, s58, 0x12000
	s_add_u32 s98, s38, 0x100000
	s_addc_u32 s99, s39, 0
	ds_read_b128 v[198:201], v157 offset:18432
	global_load_lds_dwordx4 v138, s[38:39]
	s_add_i32 m0, s58, 0x14000
	ds_read_b128 v[202:205], v157 offset:19456
	ds_read_b128 v[206:209], v157 offset:20480
	global_load_lds_dwordx4 v134, s[98:99]
	s_add_i32 m0, s58, 0x16000
	ds_read_b128 v[210:213], v157 offset:21504
	ds_read_b128 v[214:217], v157 offset:22528
	global_load_lds_dwordx4 v138, s[98:99]
	s_mov_b32 m0, s29
	ds_read_b128 v[218:221], v157 offset:23552
	global_load_lds_dwordx4 v132, s[42:43]
	s_mov_b32 m0, s31
	s_nop 0
	global_load_lds_dwordx4 v136, s[42:43]
	s_waitcnt vmcnt(9)
	s_waitcnt lgkmcnt(0)
	s_barrier
	v_mfma_f32_16x16x32_bf16 v[64:67], v[146:149], v[190:193], v[64:67]
	v_mfma_f32_16x16x32_bf16 v[64:67], v[150:153], v[194:197], v[64:67]
	v_mfma_f32_16x16x32_bf16 v[60:63], v[158:161], v[190:193], v[60:63]
	v_mfma_f32_16x16x32_bf16 v[60:63], v[162:165], v[194:197], v[60:63]
	v_mfma_f32_16x16x32_bf16 v[48:51], v[146:149], v[198:201], v[48:51]
	v_mfma_f32_16x16x32_bf16 v[48:51], v[150:153], v[202:205], v[48:51]
	v_mfma_f32_16x16x32_bf16 v[44:47], v[158:161], v[198:201], v[44:47]
	v_mfma_f32_16x16x32_bf16 v[44:47], v[162:165], v[202:205], v[44:47]
	v_mfma_f32_16x16x32_bf16 v[32:35], v[146:149], v[206:209], v[32:35]
	v_mfma_f32_16x16x32_bf16 v[32:35], v[150:153], v[210:213], v[32:35]
	v_mfma_f32_16x16x32_bf16 v[28:31], v[158:161], v[206:209], v[28:31]
	v_mfma_f32_16x16x32_bf16 v[28:31], v[162:165], v[210:213], v[28:31]
	v_mfma_f32_16x16x32_bf16 v[16:19], v[146:149], v[214:217], v[16:19]
	v_mfma_f32_16x16x32_bf16 v[16:19], v[150:153], v[218:221], v[16:19]
	v_mfma_f32_16x16x32_bf16 v[12:15], v[158:161], v[214:217], v[12:15]
	v_mfma_f32_16x16x32_bf16 v[12:15], v[162:165], v[218:221], v[12:15]
	v_mfma_f32_16x16x32_bf16 v[56:59], v[166:169], v[190:193], v[56:59]
	v_mfma_f32_16x16x32_bf16 v[56:59], v[170:173], v[194:197], v[56:59]
	v_mfma_f32_16x16x32_bf16 v[52:55], v[174:177], v[190:193], v[52:55]
	v_mfma_f32_16x16x32_bf16 v[52:55], v[186:189], v[194:197], v[52:55]
	v_mfma_f32_16x16x32_bf16 v[40:43], v[166:169], v[198:201], v[40:43]
	v_mfma_f32_16x16x32_bf16 v[40:43], v[170:173], v[202:205], v[40:43]
	v_mfma_f32_16x16x32_bf16 v[36:39], v[174:177], v[198:201], v[36:39]
	v_mfma_f32_16x16x32_bf16 v[36:39], v[186:189], v[202:205], v[36:39]
	v_mfma_f32_16x16x32_bf16 v[24:27], v[166:169], v[206:209], v[24:27]
	v_mfma_f32_16x16x32_bf16 v[24:27], v[170:173], v[210:213], v[24:27]
	v_mfma_f32_16x16x32_bf16 v[20:23], v[174:177], v[206:209], v[20:23]
	v_mfma_f32_16x16x32_bf16 v[20:23], v[186:189], v[210:213], v[20:23]
	v_mfma_f32_16x16x32_bf16 v[8:11], v[166:169], v[214:217], v[8:11]
	v_mfma_f32_16x16x32_bf16 v[8:11], v[170:173], v[218:221], v[8:11]
	v_mfma_f32_16x16x32_bf16 v[4:7], v[174:177], v[214:217], v[4:7]
	v_mfma_f32_16x16x32_bf16 v[4:7], v[186:189], v[218:221], v[4:7]
	s_barrier
	s_add_u32 s100, s42, 0x100000
	s_addc_u32 s101, s43, 0
	s_mov_b32 m0, s59
	ds_read_b128 v[146:149], v252 offset:32768
	ds_read_b128 v[150:153], v252 offset:33792
	global_load_lds_dwordx4 v132, s[100:101]
	s_mov_b32 m0, s94
	ds_read_b128 v[158:161], v252 offset:34816
	ds_read_b128 v[162:165], v252 offset:35840
	global_load_lds_dwordx4 v136, s[100:101]
	ds_read_b128 v[166:169], v252 offset:49152
	ds_read_b128 v[170:173], v252 offset:50176
	ds_read_b128 v[174:177], v252 offset:51200
	ds_read_b128 v[186:189], v252 offset:52224
	ds_read_b128 v[190:193], v157 offset:32768
	ds_read_b128 v[194:197], v157 offset:33792
	ds_read_b128 v[198:201], v157 offset:34816
	ds_read_b128 v[202:205], v157 offset:35840
	ds_read_b128 v[206:209], v157 offset:36864
	ds_read_b128 v[210:213], v157 offset:37888
	ds_read_b128 v[214:217], v157 offset:38912
	ds_read_b128 v[218:221], v157 offset:39936
	s_waitcnt vmcnt(9)
	s_mov_b32 m0, 0x21800
	s_mov_b64 exec, 0xfff
	s_waitcnt lgkmcnt(0)
	global_load_lds_dword v[242:243], off offset:128
	s_mov_b64 exec, -1
	s_barrier
	v_mfma_f32_16x16x32_bf16 v[128:131], v[146:149], v[190:193], v[128:131]
	v_mfma_f32_16x16x32_bf16 v[128:131], v[150:153], v[194:197], v[128:131]
	v_mfma_f32_16x16x32_bf16 v[124:127], v[158:161], v[190:193], v[124:127]
	v_mfma_f32_16x16x32_bf16 v[124:127], v[162:165], v[194:197], v[124:127]
	v_mfma_f32_16x16x32_bf16 v[112:115], v[146:149], v[198:201], v[112:115]
	v_mfma_f32_16x16x32_bf16 v[112:115], v[150:153], v[202:205], v[112:115]
	v_mfma_f32_16x16x32_bf16 v[108:111], v[158:161], v[198:201], v[108:111]
	v_mfma_f32_16x16x32_bf16 v[108:111], v[162:165], v[202:205], v[108:111]
	v_mfma_f32_16x16x32_bf16 v[96:99], v[146:149], v[206:209], v[96:99]
	v_mfma_f32_16x16x32_bf16 v[96:99], v[150:153], v[210:213], v[96:99]
	v_mfma_f32_16x16x32_bf16 v[92:95], v[158:161], v[206:209], v[92:95]
	v_mfma_f32_16x16x32_bf16 v[92:95], v[162:165], v[210:213], v[92:95]
	v_mfma_f32_16x16x32_bf16 v[80:83], v[146:149], v[214:217], v[80:83]
	v_mfma_f32_16x16x32_bf16 v[80:83], v[150:153], v[218:221], v[80:83]
	v_mfma_f32_16x16x32_bf16 v[76:79], v[158:161], v[214:217], v[76:79]
	v_mfma_f32_16x16x32_bf16 v[76:79], v[162:165], v[218:221], v[76:79]
	v_mfma_f32_16x16x32_bf16 v[120:123], v[166:169], v[190:193], v[120:123]
	v_mfma_f32_16x16x32_bf16 v[120:123], v[170:173], v[194:197], v[120:123]
	v_mfma_f32_16x16x32_bf16 v[116:119], v[174:177], v[190:193], v[116:119]
	v_mfma_f32_16x16x32_bf16 v[116:119], v[186:189], v[194:197], v[116:119]
	v_mfma_f32_16x16x32_bf16 v[104:107], v[166:169], v[198:201], v[104:107]
	v_mfma_f32_16x16x32_bf16 v[104:107], v[170:173], v[202:205], v[104:107]
	v_mfma_f32_16x16x32_bf16 v[100:103], v[174:177], v[198:201], v[100:103]
	v_mfma_f32_16x16x32_bf16 v[100:103], v[186:189], v[202:205], v[100:103]
	v_mfma_f32_16x16x32_bf16 v[88:91], v[166:169], v[206:209], v[88:91]
	v_mfma_f32_16x16x32_bf16 v[88:91], v[170:173], v[210:213], v[88:91]
	v_mfma_f32_16x16x32_bf16 v[84:87], v[174:177], v[206:209], v[84:87]
	v_mfma_f32_16x16x32_bf16 v[84:87], v[186:189], v[210:213], v[84:87]
	v_mfma_f32_16x16x32_bf16 v[72:75], v[166:169], v[214:217], v[72:75]
	v_mfma_f32_16x16x32_bf16 v[72:75], v[170:173], v[218:221], v[72:75]
	v_mfma_f32_16x16x32_bf16 v[68:71], v[174:177], v[214:217], v[68:71]
	v_mfma_f32_16x16x32_bf16 v[68:71], v[186:189], v[218:221], v[68:71]
	s_barrier
	s_add_u32 s38, s38, 0x80
	s_addc_u32 s39, s39, 0
	s_add_i32 m0, s58, 0x18000
	ds_read_b128 v[190:193], v157 offset:49152
	ds_read_b128 v[194:197], v157 offset:50176
	global_load_lds_dwordx4 v134, s[38:39]
	s_add_i32 m0, s58, 0x1a000
	s_add_u32 s98, s98, 0x80
	s_addc_u32 s99, s99, 0
	ds_read_b128 v[198:201], v157 offset:51200
	global_load_lds_dwordx4 v138, s[38:39]
	s_add_i32 m0, s58, 0x1c000
	ds_read_b128 v[202:205], v157 offset:52224
	ds_read_b128 v[206:209], v157 offset:53248
	global_load_lds_dwordx4 v134, s[98:99]
	s_add_i32 m0, s58, 0x1e000
	s_add_u32 s42, s42, 0x80
	s_addc_u32 s43, s43, 0
	ds_read_b128 v[210:213], v157 offset:54272
	ds_read_b128 v[214:217], v157 offset:55296
	global_load_lds_dwordx4 v138, s[98:99]
	s_mov_b32 m0, s14
	ds_read_b128 v[218:221], v157 offset:56320
	global_load_lds_dwordx4 v132, s[42:43]
	s_mov_b32 m0, s15
	s_nop 0
	global_load_lds_dwordx4 v136, s[42:43]
	s_waitcnt vmcnt(9)
	s_waitcnt lgkmcnt(0)
	s_barrier
	v_mfma_f32_16x16x32_bf16 v[64:67], v[146:149], v[190:193], v[64:67]
	v_mfma_f32_16x16x32_bf16 v[64:67], v[150:153], v[194:197], v[64:67]
	v_mfma_f32_16x16x32_bf16 v[60:63], v[158:161], v[190:193], v[60:63]
	v_mfma_f32_16x16x32_bf16 v[60:63], v[162:165], v[194:197], v[60:63]
	v_mfma_f32_16x16x32_bf16 v[48:51], v[146:149], v[198:201], v[48:51]
	v_mfma_f32_16x16x32_bf16 v[48:51], v[150:153], v[202:205], v[48:51]
	v_mfma_f32_16x16x32_bf16 v[44:47], v[158:161], v[198:201], v[44:47]
	v_mfma_f32_16x16x32_bf16 v[44:47], v[162:165], v[202:205], v[44:47]
	v_mfma_f32_16x16x32_bf16 v[32:35], v[146:149], v[206:209], v[32:35]
	v_mfma_f32_16x16x32_bf16 v[32:35], v[150:153], v[210:213], v[32:35]
	v_mfma_f32_16x16x32_bf16 v[28:31], v[158:161], v[206:209], v[28:31]
	v_mfma_f32_16x16x32_bf16 v[28:31], v[162:165], v[210:213], v[28:31]
	v_mfma_f32_16x16x32_bf16 v[16:19], v[146:149], v[214:217], v[16:19]
	v_mfma_f32_16x16x32_bf16 v[16:19], v[150:153], v[218:221], v[16:19]
	v_mfma_f32_16x16x32_bf16 v[12:15], v[158:161], v[214:217], v[12:15]
	v_mfma_f32_16x16x32_bf16 v[12:15], v[162:165], v[218:221], v[12:15]
	v_mfma_f32_16x16x32_bf16 v[56:59], v[166:169], v[190:193], v[56:59]
	v_mfma_f32_16x16x32_bf16 v[56:59], v[170:173], v[194:197], v[56:59]
	v_mfma_f32_16x16x32_bf16 v[52:55], v[174:177], v[190:193], v[52:55]
	v_mfma_f32_16x16x32_bf16 v[52:55], v[186:189], v[194:197], v[52:55]
	v_mfma_f32_16x16x32_bf16 v[40:43], v[166:169], v[198:201], v[40:43]
	v_mfma_f32_16x16x32_bf16 v[40:43], v[170:173], v[202:205], v[40:43]
	v_mfma_f32_16x16x32_bf16 v[36:39], v[174:177], v[198:201], v[36:39]
	v_mfma_f32_16x16x32_bf16 v[36:39], v[186:189], v[202:205], v[36:39]
	v_mfma_f32_16x16x32_bf16 v[24:27], v[166:169], v[206:209], v[24:27]
	v_mfma_f32_16x16x32_bf16 v[24:27], v[170:173], v[210:213], v[24:27]
	v_mfma_f32_16x16x32_bf16 v[20:23], v[174:177], v[206:209], v[20:23]
	v_mfma_f32_16x16x32_bf16 v[20:23], v[186:189], v[210:213], v[20:23]
	v_mfma_f32_16x16x32_bf16 v[8:11], v[166:169], v[214:217], v[8:11]
	v_mfma_f32_16x16x32_bf16 v[8:11], v[170:173], v[218:221], v[8:11]
	v_mfma_f32_16x16x32_bf16 v[4:7], v[174:177], v[214:217], v[4:7]
	v_mfma_f32_16x16x32_bf16 v[4:7], v[186:189], v[218:221], v[4:7]
	s_barrier
	s_add_i32 s12, s12, 2
	s_add_u32 s10, s10, 0x100
	s_addc_u32 s11, s11, 0
	s_add_u32 s0, s0, 0x100
	s_addc_u32 s1, s1, 0
	s_cmp_gt_u32 s12, 61
	s_cbranch_scc0 .LBB0_882
	s_and_b64 vcc, exec, s[48:49]
	s_cbranch_vccz .LBB0_885
	s_barrier

.LBB0_1225:
	s_and_b32 s98, s59, 3
	s_and_b32 s99, s58, 7
	s_lshl_b32 s98, s98, 6
	s_lshl_b32 s99, s99, 5
	v_and_b32_e32 v244, 63, v0
	v_mul_u32_u24_e32 v245, 86, v244
	v_lshrrev_b32_e32 v245, 10, v245
	v_mul_u32_u24_e32 v245, 12, v245
	v_sub_u32_e32 v244, v244, v245
	v_lshrrev_b32_e32 v245, 6, v0
	v_mad_u32_u24 v244, v245, 12, v244
	v_cmp_gt_u32_e32 vcc, 64, v244
	v_add_u32_e32 v245, s98, v244
	v_subrev_u32_e32 v247, 64, v244
	v_add_u32_e32 v248, s99, v247
	v_cndmask_b32_e32 v245, v248, v245, vcc
	v_lshlrev_b32_e32 v245, 13, v245
	v_add_u32_e32 v244, 0x80, v245
	v_mov_b32_e32 v245, 0
	v_mov_b32_e32 v246, s10
	v_mov_b32_e32 v247, s11
	v_mov_b32_e32 v248, s28
	v_mov_b32_e32 v249, s29
	v_cndmask_b32_e32 v246, v248, v246, vcc
	v_cndmask_b32_e32 v247, v249, v247, vcc
	v_lshl_add_u64 v[242:243], v[246:247], 0, v[244:245]
	v_add_u32_e32 v252, 0x10000, v151
	s_add_u32 s10, s10, 0x100080
	s_addc_u32 s11, s11, 0
	s_add_u32 s0, s28, 0x100
	v_mov_b32_e32 v4, 0
	s_addc_u32 s1, s29, 0
	s_mov_b32 s20, -2
	v_mov_b32_e32 v5, v4
	v_mov_b32_e32 v6, v4
	v_mov_b32_e32 v7, v4
	v_mov_b32_e32 v8, v4
	v_mov_b32_e32 v9, v4
	v_mov_b32_e32 v10, v4
	v_mov_b32_e32 v11, v4
	v_mov_b32_e32 v20, v4
	v_mov_b32_e32 v21, v4
	v_mov_b32_e32 v22, v4
	v_mov_b32_e32 v23, v4
	v_mov_b32_e32 v24, v4
	v_mov_b32_e32 v25, v4
	v_mov_b32_e32 v26, v4
	v_mov_b32_e32 v27, v4
	v_mov_b32_e32 v36, v4
	v_mov_b32_e32 v37, v4
	v_mov_b32_e32 v38, v4
	v_mov_b32_e32 v39, v4
	v_mov_b32_e32 v40, v4
	v_mov_b32_e32 v41, v4
	v_mov_b32_e32 v42, v4
	v_mov_b32_e32 v43, v4
	v_mov_b32_e32 v52, v4
	v_mov_b32_e32 v53, v4
	v_mov_b32_e32 v54, v4
	v_mov_b32_e32 v55, v4
	v_mov_b32_e32 v56, v4
	v_mov_b32_e32 v57, v4
	v_mov_b32_e32 v58, v4
	v_mov_b32_e32 v59, v4
	v_mov_b32_e32 v12, v4
	v_mov_b32_e32 v13, v4
	v_mov_b32_e32 v14, v4
	v_mov_b32_e32 v15, v4
	v_mov_b32_e32 v16, v4
	v_mov_b32_e32 v17, v4
	v_mov_b32_e32 v18, v4
	v_mov_b32_e32 v19, v4
	v_mov_b32_e32 v28, v4
	v_mov_b32_e32 v29, v4
	v_mov_b32_e32 v30, v4
	v_mov_b32_e32 v31, v4
	v_mov_b32_e32 v32, v4
	v_mov_b32_e32 v33, v4
	v_mov_b32_e32 v34, v4
	v_mov_b32_e32 v35, v4
	v_mov_b32_e32 v44, v4
	v_mov_b32_e32 v45, v4
	v_mov_b32_e32 v46, v4
	v_mov_b32_e32 v47, v4
	v_mov_b32_e32 v48, v4
	v_mov_b32_e32 v49, v4
	v_mov_b32_e32 v50, v4
	v_mov_b32_e32 v51, v4
	v_mov_b32_e32 v60, v4
	v_mov_b32_e32 v61, v4
	v_mov_b32_e32 v62, v4
	v_mov_b32_e32 v63, v4
	v_mov_b32_e32 v64, v4
	v_mov_b32_e32 v65, v4
	v_mov_b32_e32 v66, v4
	v_mov_b32_e32 v67, v4
	v_mov_b32_e32 v68, v4
	v_mov_b32_e32 v69, v4
	v_mov_b32_e32 v70, v4
	v_mov_b32_e32 v71, v4
	v_mov_b32_e32 v72, v4
	v_mov_b32_e32 v73, v4
	v_mov_b32_e32 v74, v4
	v_mov_b32_e32 v75, v4
	v_mov_b32_e32 v84, v4
	v_mov_b32_e32 v85, v4
	v_mov_b32_e32 v86, v4
	v_mov_b32_e32 v87, v4
	v_mov_b32_e32 v88, v4
	v_mov_b32_e32 v89, v4
	v_mov_b32_e32 v90, v4
	v_mov_b32_e32 v91, v4
	v_mov_b32_e32 v100, v4
	v_mov_b32_e32 v101, v4
	v_mov_b32_e32 v102, v4
	v_mov_b32_e32 v103, v4
	v_mov_b32_e32 v104, v4
	v_mov_b32_e32 v105, v4
	v_mov_b32_e32 v106, v4
	v_mov_b32_e32 v107, v4
	v_mov_b32_e32 v116, v4
	v_mov_b32_e32 v117, v4
	v_mov_b32_e32 v118, v4
	v_mov_b32_e32 v119, v4
	v_mov_b32_e32 v120, v4
	v_mov_b32_e32 v121, v4
	v_mov_b32_e32 v122, v4
	v_mov_b32_e32 v123, v4
	v_mov_b32_e32 v76, v4
	v_mov_b32_e32 v77, v4
	v_mov_b32_e32 v78, v4
	v_mov_b32_e32 v79, v4
	v_mov_b32_e32 v80, v4
	v_mov_b32_e32 v81, v4
	v_mov_b32_e32 v82, v4
	v_mov_b32_e32 v83, v4
	v_mov_b32_e32 v92, v4
	v_mov_b32_e32 v93, v4
	v_mov_b32_e32 v94, v4
	v_mov_b32_e32 v95, v4
	v_mov_b32_e32 v96, v4
	v_mov_b32_e32 v97, v4
	v_mov_b32_e32 v98, v4
	v_mov_b32_e32 v99, v4
	v_mov_b32_e32 v108, v4
	v_mov_b32_e32 v109, v4
	v_mov_b32_e32 v110, v4
	v_mov_b32_e32 v111, v4
	v_mov_b32_e32 v112, v4
	v_mov_b32_e32 v113, v4
	v_mov_b32_e32 v114, v4
	v_mov_b32_e32 v115, v4
	v_mov_b32_e32 v124, v4
	v_mov_b32_e32 v125, v4
	v_mov_b32_e32 v126, v4
	v_mov_b32_e32 v127, v4
	v_mov_b32_e32 v128, v4
	v_mov_b32_e32 v129, v4
	v_mov_b32_e32 v130, v4
	v_mov_b32_e32 v131, v4
.LBB0_1226:
	s_add_u32 s21, s10, 0xfff00080
	s_addc_u32 s22, s11, -1
	s_cmp_eq_u32 s20, 60
	s_cselect_b32 s31, s53, s22
	s_cselect_b32 s30, s52, s21
	s_cselect_b32 s29, s55, s1
	s_cselect_b32 s28, s54, s0
	s_cmp_lt_i32 s20, 58
	s_cselect_b32 s100, 0x100, 0
	s_mov_b32 s101, 0
	v_lshl_add_u64 v[242:243], v[242:243], 0, s[100:101]
	s_add_i32 m0, s8, 0xc000
	ds_read_b128 v[144:147], v252
	ds_read_b128 v[154:157], v252 offset:1024
	global_load_lds_dwordx4 v140, s[10:11]
	s_add_i32 m0, s8, 0xe000
	ds_read_b128 v[158:161], v252 offset:2048
	ds_read_b128 v[162:165], v252 offset:3072
	global_load_lds_dwordx4 v142, s[10:11]
	ds_read_b128 v[166:169], v252 offset:16384
	ds_read_b128 v[170:173], v252 offset:17408
	ds_read_b128 v[174:177], v252 offset:18432
	ds_read_b128 v[186:189], v252 offset:19456
	ds_read_b128 v[190:193], v153
	ds_read_b128 v[194:197], v153 offset:1024
	ds_read_b128 v[198:201], v153 offset:2048
	ds_read_b128 v[202:205], v153 offset:3072
	ds_read_b128 v[206:209], v153 offset:4096
	ds_read_b128 v[210:213], v153 offset:5120
	ds_read_b128 v[214:217], v153 offset:6144
	ds_read_b128 v[218:221], v153 offset:7168
	s_waitcnt vmcnt(9)
	s_mov_b32 m0, 0x21800
	s_mov_b64 exec, 0xfff
	s_waitcnt lgkmcnt(0)
	global_load_lds_dword v[242:243], off
	s_mov_b64 exec, -1
	s_barrier
	v_mfma_f32_16x16x32_bf16 v[128:131], v[144:147], v[190:193], v[128:131]
	v_mfma_f32_16x16x32_bf16 v[128:131], v[154:157], v[194:197], v[128:131]
	v_mfma_f32_16x16x32_bf16 v[124:127], v[158:161], v[190:193], v[124:127]
	v_mfma_f32_16x16x32_bf16 v[124:127], v[162:165], v[194:197], v[124:127]
	v_mfma_f32_16x16x32_bf16 v[112:115], v[144:147], v[198:201], v[112:115]
	v_mfma_f32_16x16x32_bf16 v[112:115], v[154:157], v[202:205], v[112:115]
	v_mfma_f32_16x16x32_bf16 v[108:111], v[158:161], v[198:201], v[108:111]
	v_mfma_f32_16x16x32_bf16 v[108:111], v[162:165], v[202:205], v[108:111]
	v_mfma_f32_16x16x32_bf16 v[96:99], v[144:147], v[206:209], v[96:99]
	v_mfma_f32_16x16x32_bf16 v[96:99], v[154:157], v[210:213], v[96:99]
	v_mfma_f32_16x16x32_bf16 v[92:95], v[158:161], v[206:209], v[92:95]
	v_mfma_f32_16x16x32_bf16 v[92:95], v[162:165], v[210:213], v[92:95]
	v_mfma_f32_16x16x32_bf16 v[80:83], v[144:147], v[214:217], v[80:83]
	v_mfma_f32_16x16x32_bf16 v[80:83], v[154:157], v[218:221], v[80:83]
	v_mfma_f32_16x16x32_bf16 v[76:79], v[158:161], v[214:217], v[76:79]
	v_mfma_f32_16x16x32_bf16 v[76:79], v[162:165], v[218:221], v[76:79]
	v_mfma_f32_16x16x32_bf16 v[120:123], v[166:169], v[190:193], v[120:123]
	v_mfma_f32_16x16x32_bf16 v[120:123], v[170:173], v[194:197], v[120:123]
	v_mfma_f32_16x16x32_bf16 v[116:119], v[174:177], v[190:193], v[116:119]
	v_mfma_f32_16x16x32_bf16 v[116:119], v[186:189], v[194:197], v[116:119]
	v_mfma_f32_16x16x32_bf16 v[104:107], v[166:169], v[198:201], v[104:107]
	v_mfma_f32_16x16x32_bf16 v[104:107], v[170:173], v[202:205], v[104:107]
	v_mfma_f32_16x16x32_bf16 v[100:103], v[174:177], v[198:201], v[100:103]
	v_mfma_f32_16x16x32_bf16 v[100:103], v[186:189], v[202:205], v[100:103]
	v_mfma_f32_16x16x32_bf16 v[88:91], v[166:169], v[206:209], v[88:91]
	v_mfma_f32_16x16x32_bf16 v[88:91], v[170:173], v[210:213], v[88:91]
	v_mfma_f32_16x16x32_bf16 v[84:87], v[174:177], v[206:209], v[84:87]
	v_mfma_f32_16x16x32_bf16 v[84:87], v[186:189], v[210:213], v[84:87]
	v_mfma_f32_16x16x32_bf16 v[72:75], v[166:169], v[214:217], v[72:75]
	v_mfma_f32_16x16x32_bf16 v[72:75], v[170:173], v[218:221], v[72:75]
	v_mfma_f32_16x16x32_bf16 v[68:71], v[174:177], v[214:217], v[68:71]
	v_mfma_f32_16x16x32_bf16 v[68:71], v[186:189], v[218:221], v[68:71]
	s_barrier
	s_add_i32 m0, s38, 0x10000
	ds_read_b128 v[190:193], v153 offset:16384
	ds_read_b128 v[194:197], v153 offset:17408
	global_load_lds_dwordx4 v136, s[28:29]
	s_add_i32 m0, s38, 0x12000
	s_add_u32 s98, s28, 0x100000
	s_addc_u32 s99, s29, 0
	ds_read_b128 v[198:201], v153 offset:18432
	global_load_lds_dwordx4 v132, s[28:29]
	s_add_i32 m0, s38, 0x14000
	ds_read_b128 v[202:205], v153 offset:19456
	ds_read_b128 v[206:209], v153 offset:20480
	global_load_lds_dwordx4 v136, s[98:99]
	s_add_i32 m0, s38, 0x16000
	ds_read_b128 v[210:213], v153 offset:21504
	ds_read_b128 v[214:217], v153 offset:22528
	global_load_lds_dwordx4 v132, s[98:99]
	s_mov_b32 m0, s8
	ds_read_b128 v[218:221], v153 offset:23552
	global_load_lds_dwordx4 v138, s[30:31]
	s_mov_b32 m0, s9
	s_nop 0
	global_load_lds_dwordx4 v134, s[30:31]
	s_waitcnt vmcnt(9)
	s_waitcnt lgkmcnt(0)
	s_barrier
	v_mfma_f32_16x16x32_bf16 v[64:67], v[144:147], v[190:193], v[64:67]
	v_mfma_f32_16x16x32_bf16 v[64:67], v[154:157], v[194:197], v[64:67]
	v_mfma_f32_16x16x32_bf16 v[60:63], v[158:161], v[190:193], v[60:63]
	v_mfma_f32_16x16x32_bf16 v[60:63], v[162:165], v[194:197], v[60:63]
	v_mfma_f32_16x16x32_bf16 v[48:51], v[144:147], v[198:201], v[48:51]
	v_mfma_f32_16x16x32_bf16 v[48:51], v[154:157], v[202:205], v[48:51]
	v_mfma_f32_16x16x32_bf16 v[44:47], v[158:161], v[198:201], v[44:47]
	v_mfma_f32_16x16x32_bf16 v[44:47], v[162:165], v[202:205], v[44:47]
	v_mfma_f32_16x16x32_bf16 v[32:35], v[144:147], v[206:209], v[32:35]
	v_mfma_f32_16x16x32_bf16 v[32:35], v[154:157], v[210:213], v[32:35]
	v_mfma_f32_16x16x32_bf16 v[28:31], v[158:161], v[206:209], v[28:31]
	v_mfma_f32_16x16x32_bf16 v[28:31], v[162:165], v[210:213], v[28:31]
	v_mfma_f32_16x16x32_bf16 v[16:19], v[144:147], v[214:217], v[16:19]
	v_mfma_f32_16x16x32_bf16 v[16:19], v[154:157], v[218:221], v[16:19]
	v_mfma_f32_16x16x32_bf16 v[12:15], v[158:161], v[214:217], v[12:15]
	v_mfma_f32_16x16x32_bf16 v[12:15], v[162:165], v[218:221], v[12:15]
	v_mfma_f32_16x16x32_bf16 v[56:59], v[166:169], v[190:193], v[56:59]
	v_mfma_f32_16x16x32_bf16 v[56:59], v[170:173], v[194:197], v[56:59]
	v_mfma_f32_16x16x32_bf16 v[52:55], v[174:177], v[190:193], v[52:55]
	v_mfma_f32_16x16x32_bf16 v[52:55], v[186:189], v[194:197], v[52:55]
	v_mfma_f32_16x16x32_bf16 v[40:43], v[166:169], v[198:201], v[40:43]
	v_mfma_f32_16x16x32_bf16 v[40:43], v[170:173], v[202:205], v[40:43]
	v_mfma_f32_16x16x32_bf16 v[36:39], v[174:177], v[198:201], v[36:39]
	v_mfma_f32_16x16x32_bf16 v[36:39], v[186:189], v[202:205], v[36:39]
	v_mfma_f32_16x16x32_bf16 v[24:27], v[166:169], v[206:209], v[24:27]
	v_mfma_f32_16x16x32_bf16 v[24:27], v[170:173], v[210:213], v[24:27]
	v_mfma_f32_16x16x32_bf16 v[20:23], v[174:177], v[206:209], v[20:23]
	v_mfma_f32_16x16x32_bf16 v[20:23], v[186:189], v[210:213], v[20:23]
	v_mfma_f32_16x16x32_bf16 v[8:11], v[166:169], v[214:217], v[8:11]
	v_mfma_f32_16x16x32_bf16 v[8:11], v[170:173], v[218:221], v[8:11]
	v_mfma_f32_16x16x32_bf16 v[4:7], v[174:177], v[214:217], v[4:7]
	v_mfma_f32_16x16x32_bf16 v[4:7], v[186:189], v[218:221], v[4:7]
	s_barrier
	s_add_u32 s100, s30, 0x100000
	s_addc_u32 s101, s31, 0
	s_mov_b32 m0, s16
	ds_read_b128 v[144:147], v252 offset:32768
	ds_read_b128 v[154:157], v252 offset:33792
	global_load_lds_dwordx4 v138, s[100:101]
	s_mov_b32 m0, s17
	ds_read_b128 v[158:161], v252 offset:34816
	ds_read_b128 v[162:165], v252 offset:35840
	global_load_lds_dwordx4 v134, s[100:101]
	ds_read_b128 v[166:169], v252 offset:49152
	ds_read_b128 v[170:173], v252 offset:50176
	ds_read_b128 v[174:177], v252 offset:51200
	ds_read_b128 v[186:189], v252 offset:52224
	ds_read_b128 v[190:193], v153 offset:32768
	ds_read_b128 v[194:197], v153 offset:33792
	ds_read_b128 v[198:201], v153 offset:34816
	ds_read_b128 v[202:205], v153 offset:35840
	ds_read_b128 v[206:209], v153 offset:36864
	ds_read_b128 v[210:213], v153 offset:37888
	ds_read_b128 v[214:217], v153 offset:38912
	ds_read_b128 v[218:221], v153 offset:39936
	s_waitcnt vmcnt(9)
	s_mov_b32 m0, 0x21800
	s_mov_b64 exec, 0xfff
	s_waitcnt lgkmcnt(0)
	global_load_lds_dword v[242:243], off offset:128
	s_mov_b64 exec, -1
	s_barrier
	v_mfma_f32_16x16x32_bf16 v[128:131], v[144:147], v[190:193], v[128:131]
	v_mfma_f32_16x16x32_bf16 v[128:131], v[154:157], v[194:197], v[128:131]
	v_mfma_f32_16x16x32_bf16 v[124:127], v[158:161], v[190:193], v[124:127]
	v_mfma_f32_16x16x32_bf16 v[124:127], v[162:165], v[194:197], v[124:127]
	v_mfma_f32_16x16x32_bf16 v[112:115], v[144:147], v[198:201], v[112:115]
	v_mfma_f32_16x16x32_bf16 v[112:115], v[154:157], v[202:205], v[112:115]
	v_mfma_f32_16x16x32_bf16 v[108:111], v[158:161], v[198:201], v[108:111]
	v_mfma_f32_16x16x32_bf16 v[108:111], v[162:165], v[202:205], v[108:111]
	v_mfma_f32_16x16x32_bf16 v[96:99], v[144:147], v[206:209], v[96:99]
	v_mfma_f32_16x16x32_bf16 v[96:99], v[154:157], v[210:213], v[96:99]
	v_mfma_f32_16x16x32_bf16 v[92:95], v[158:161], v[206:209], v[92:95]
	v_mfma_f32_16x16x32_bf16 v[92:95], v[162:165], v[210:213], v[92:95]
	v_mfma_f32_16x16x32_bf16 v[80:83], v[144:147], v[214:217], v[80:83]
	v_mfma_f32_16x16x32_bf16 v[80:83], v[154:157], v[218:221], v[80:83]
	v_mfma_f32_16x16x32_bf16 v[76:79], v[158:161], v[214:217], v[76:79]
	v_mfma_f32_16x16x32_bf16 v[76:79], v[162:165], v[218:221], v[76:79]
	v_mfma_f32_16x16x32_bf16 v[120:123], v[166:169], v[190:193], v[120:123]
	v_mfma_f32_16x16x32_bf16 v[120:123], v[170:173], v[194:197], v[120:123]
	v_mfma_f32_16x16x32_bf16 v[116:119], v[174:177], v[190:193], v[116:119]
	v_mfma_f32_16x16x32_bf16 v[116:119], v[186:189], v[194:197], v[116:119]
	v_mfma_f32_16x16x32_bf16 v[104:107], v[166:169], v[198:201], v[104:107]
	v_mfma_f32_16x16x32_bf16 v[104:107], v[170:173], v[202:205], v[104:107]
	v_mfma_f32_16x16x32_bf16 v[100:103], v[174:177], v[198:201], v[100:103]
	v_mfma_f32_16x16x32_bf16 v[100:103], v[186:189], v[202:205], v[100:103]
	v_mfma_f32_16x16x32_bf16 v[88:91], v[166:169], v[206:209], v[88:91]
	v_mfma_f32_16x16x32_bf16 v[88:91], v[170:173], v[210:213], v[88:91]
	v_mfma_f32_16x16x32_bf16 v[84:87], v[174:177], v[206:209], v[84:87]
	v_mfma_f32_16x16x32_bf16 v[84:87], v[186:189], v[210:213], v[84:87]
	v_mfma_f32_16x16x32_bf16 v[72:75], v[166:169], v[214:217], v[72:75]
	v_mfma_f32_16x16x32_bf16 v[72:75], v[170:173], v[218:221], v[72:75]
	v_mfma_f32_16x16x32_bf16 v[68:71], v[174:177], v[214:217], v[68:71]
	v_mfma_f32_16x16x32_bf16 v[68:71], v[186:189], v[218:221], v[68:71]
	s_barrier
	s_add_u32 s28, s28, 0x80
	s_addc_u32 s29, s29, 0
	s_add_i32 m0, s38, 0x18000
	ds_read_b128 v[190:193], v153 offset:49152
	ds_read_b128 v[194:197], v153 offset:50176
	global_load_lds_dwordx4 v136, s[28:29]
	s_add_i32 m0, s38, 0x1a000
	s_add_u32 s98, s98, 0x80
	s_addc_u32 s99, s99, 0
	ds_read_b128 v[198:201], v153 offset:51200
	global_load_lds_dwordx4 v132, s[28:29]
	s_add_i32 m0, s38, 0x1c000
	ds_read_b128 v[202:205], v153 offset:52224
	ds_read_b128 v[206:209], v153 offset:53248
	global_load_lds_dwordx4 v136, s[98:99]
	s_add_i32 m0, s38, 0x1e000
	s_add_u32 s30, s30, 0x80
	s_addc_u32 s31, s31, 0
	ds_read_b128 v[210:213], v153 offset:54272
	ds_read_b128 v[214:217], v153 offset:55296
	global_load_lds_dwordx4 v132, s[98:99]
	s_mov_b32 m0, s45
	ds_read_b128 v[218:221], v153 offset:56320
	global_load_lds_dwordx4 v138, s[30:31]
	s_mov_b32 m0, s46
	s_nop 0
	global_load_lds_dwordx4 v134, s[30:31]
	s_waitcnt vmcnt(9)
	s_waitcnt lgkmcnt(0)
	s_barrier
	v_mfma_f32_16x16x32_bf16 v[64:67], v[144:147], v[190:193], v[64:67]
	v_mfma_f32_16x16x32_bf16 v[64:67], v[154:157], v[194:197], v[64:67]
	v_mfma_f32_16x16x32_bf16 v[60:63], v[158:161], v[190:193], v[60:63]
	v_mfma_f32_16x16x32_bf16 v[60:63], v[162:165], v[194:197], v[60:63]
	v_mfma_f32_16x16x32_bf16 v[48:51], v[144:147], v[198:201], v[48:51]
	v_mfma_f32_16x16x32_bf16 v[48:51], v[154:157], v[202:205], v[48:51]
	v_mfma_f32_16x16x32_bf16 v[44:47], v[158:161], v[198:201], v[44:47]
	v_mfma_f32_16x16x32_bf16 v[44:47], v[162:165], v[202:205], v[44:47]
	v_mfma_f32_16x16x32_bf16 v[32:35], v[144:147], v[206:209], v[32:35]
	v_mfma_f32_16x16x32_bf16 v[32:35], v[154:157], v[210:213], v[32:35]
	v_mfma_f32_16x16x32_bf16 v[28:31], v[158:161], v[206:209], v[28:31]
	v_mfma_f32_16x16x32_bf16 v[28:31], v[162:165], v[210:213], v[28:31]
	v_mfma_f32_16x16x32_bf16 v[16:19], v[144:147], v[214:217], v[16:19]
	v_mfma_f32_16x16x32_bf16 v[16:19], v[154:157], v[218:221], v[16:19]
	v_mfma_f32_16x16x32_bf16 v[12:15], v[158:161], v[214:217], v[12:15]
	v_mfma_f32_16x16x32_bf16 v[12:15], v[162:165], v[218:221], v[12:15]
	v_mfma_f32_16x16x32_bf16 v[56:59], v[166:169], v[190:193], v[56:59]
	v_mfma_f32_16x16x32_bf16 v[56:59], v[170:173], v[194:197], v[56:59]
	v_mfma_f32_16x16x32_bf16 v[52:55], v[174:177], v[190:193], v[52:55]
	v_mfma_f32_16x16x32_bf16 v[52:55], v[186:189], v[194:197], v[52:55]
	v_mfma_f32_16x16x32_bf16 v[40:43], v[166:169], v[198:201], v[40:43]
	v_mfma_f32_16x16x32_bf16 v[40:43], v[170:173], v[202:205], v[40:43]
	v_mfma_f32_16x16x32_bf16 v[36:39], v[174:177], v[198:201], v[36:39]
	v_mfma_f32_16x16x32_bf16 v[36:39], v[186:189], v[202:205], v[36:39]
	v_mfma_f32_16x16x32_bf16 v[24:27], v[166:169], v[206:209], v[24:27]
	v_mfma_f32_16x16x32_bf16 v[24:27], v[170:173], v[210:213], v[24:27]
	v_mfma_f32_16x16x32_bf16 v[20:23], v[174:177], v[206:209], v[20:23]
	v_mfma_f32_16x16x32_bf16 v[20:23], v[186:189], v[210:213], v[20:23]
	v_mfma_f32_16x16x32_bf16 v[8:11], v[166:169], v[214:217], v[8:11]
	v_mfma_f32_16x16x32_bf16 v[8:11], v[170:173], v[218:221], v[8:11]
	v_mfma_f32_16x16x32_bf16 v[4:7], v[174:177], v[214:217], v[4:7]
	v_mfma_f32_16x16x32_bf16 v[4:7], v[186:189], v[218:221], v[4:7]
	s_barrier
	s_add_i32 s20, s20, 2
	s_add_u32 s10, s10, 0x100
	s_addc_u32 s11, s11, 0
	s_add_u32 s0, s0, 0x100
	s_addc_u32 s1, s1, 0
	s_cmp_gt_u32 s20, 61
	s_cbranch_scc0 .LBB0_1226
	s_and_b64 vcc, exec, s[48:49]
	s_cbranch_vccz .LBB0_1229
	s_barrier
